# redundant s_waitcnt lgkmcnt(0) at the head of every MFMA segment removed (the same wait stands in front of the barrier); flips deleted
# baseline (speedup 1.0000x reference)
; #define PG8_STAGE(bufoff, gbase, voff) do { _Pragma("unroll") for (int _i = 0; _i < 2; ++_i) \
;         __builtin_amdgcn_global_load_lds((const unsigned*)((const char*)(gbase) + (voff)[_i]), (LAS unsigned*)(lds + (bufoff) + ldsw + _i * 8192), 16, 0, 0); } while (0)
; #define PG8_LDA(dst, b, h) do { _Pragma("unroll") for (int m = 0; m < 4; ++m) _Pragma("unroll") for (int k = 0; k < 2; ++k) dst[m][k] = *(const LAS bf16x8*)(lds + PG8_SA(b, h) + aoff + m * 2048 + k * 1024); } while (0)
; #define PG8_LDB(dst, b, h) do { _Pragma("unroll") for (int n = 0; n < 2; ++n) _Pragma("unroll") for (int k = 0; k < 2; ++k) dst[n][k] = *(const LAS bf16x8*)(lds + PG8_SB(b, h) + boff + n * 2048 + k * 1024); } while (0)
; #define PG8_WAIT_V(n) asm volatile("s_waitcnt vmcnt(" #n ")" ::: "memory")
; #define PG8_WAIT_L(n) asm volatile("s_waitcnt lgkmcnt(" #n ")" ::: "memory")
; #define PG8_BAR __builtin_amdgcn_s_barrier()
; #define PG8_SCHED __builtin_amdgcn_sched_barrier(0)
; template <class Epi, class Geom, class Sched, bool ALIGN_EPI, bool I8 = false>
; __device__ __forceinline__ void gemm_phase(LAS unsigned char* lds, const Gemm g, const Sched& S, const Epi& E) {
;     ...
;             PG8_LDB(B0, 0, 0); PG8_LDB(B1, 0, 1); PG8_SCHED; PG8_LDA(At, 0, 0); PG8_STAGE(PG8_SA(1, 1), a1 + hsA, voffA);
;             PG8_WAIT_V(8); PG8_WAIT_L(0); PG8_BAR; PG8_MMA(0, 0, At, B0); PG8_MMA(0, 1, At, B1); PG8_BAR; PG8_SCHED;
;             PG8_LDA(At, 0, 1); PG8_STAGE(PG8_SB(0, 0), b2, voffB); PG8_STAGE(PG8_SB(0, 1), b2 + hsB, voffB); PG8_STAGE(PG8_SA(0, 0), a2, voffA);
;             PG8_WAIT_V(8); PG8_WAIT_L(0); PG8_BAR; PG8_MMA(1, 0, At, B0); PG8_MMA(1, 1, At, B1); PG8_BAR; PG8_SCHED;
.LBB0_194:
	ds_read_b128 v[106:109], v241
	ds_read_b128 v[110:113], v241 offset:1024
	ds_read_b128 v[138:141], v241 offset:2048
	ds_read_b128 v[142:145], v241 offset:3072
	ds_read_b128 v[146:149], v242
	ds_read_b128 v[150:153], v242 offset:1024
	ds_read_b128 v[154:157], v242 offset:2048
	ds_read_b128 v[158:161], v242 offset:3072
	s_add_u32 s4, s0, 0xfff00080
	s_addc_u32 s5, s1, -1
	s_cmp_eq_u32 s13, 60
	s_cselect_b32 s7, s3, s5
	s_cselect_b32 s6, s8, s4
	s_cselect_b32 s5, s9, s12
	s_cselect_b32 s4, s10, s11
	v_lshl_add_u64 v[208:209], s[0:1], 0, v[184:185]
	s_add_i32 m0, s73, 0xc000
	ds_read_b128 v[162:165], v243
	ds_read_b128 v[166:169], v243 offset:1024
	ds_read_b128 v[170:173], v243 offset:2048
	ds_read_b128 v[188:191], v243 offset:3072
	ds_read_b128 v[192:195], v243 offset:4096
	ds_read_b128 v[196:199], v243 offset:5120
	ds_read_b128 v[200:203], v243 offset:6144
	ds_read_b128 v[204:207], v243 offset:7168
	global_load_lds_dwordx4 v[208:209], off
	v_lshl_add_u64 v[208:209], s[0:1], 0, v[186:187]
	s_add_i32 m0, s73, 0xe000
	s_nop 0
	global_load_lds_dwordx4 v[208:209], off
	s_waitcnt vmcnt(8)
	s_waitcnt lgkmcnt(0)
	s_barrier
	v_mfma_f32_16x16x32_bf16 v[122:125], v[106:109], v[162:165], v[122:125]
	v_mfma_f32_16x16x32_bf16 v[126:129], v[138:141], v[162:165], v[126:129]
	v_mfma_f32_16x16x32_bf16 v[102:105], v[106:109], v[170:173], v[102:105]
	v_mfma_f32_16x16x32_bf16 v[98:101], v[138:141], v[170:173], v[98:101]
	v_mfma_f32_16x16x32_bf16 v[94:97], v[106:109], v[192:195], v[94:97]
	v_mfma_f32_16x16x32_bf16 v[86:89], v[138:141], v[192:195], v[86:89]
	v_mfma_f32_16x16x32_bf16 v[78:81], v[106:109], v[200:203], v[78:81]
	v_mfma_f32_16x16x32_bf16 v[70:73], v[138:141], v[200:203], v[70:73]
	v_mfma_f32_16x16x32_bf16 v[122:125], v[110:113], v[166:169], v[122:125]
	v_mfma_f32_16x16x32_bf16 v[126:129], v[142:145], v[166:169], v[126:129]
	v_mfma_f32_16x16x32_bf16 v[102:105], v[110:113], v[188:191], v[102:105]
	v_mfma_f32_16x16x32_bf16 v[98:101], v[142:145], v[188:191], v[98:101]
	v_mfma_f32_16x16x32_bf16 v[94:97], v[110:113], v[196:199], v[94:97]
	v_mfma_f32_16x16x32_bf16 v[86:89], v[142:145], v[196:199], v[86:89]
	v_mfma_f32_16x16x32_bf16 v[78:81], v[110:113], v[204:207], v[78:81]
	v_mfma_f32_16x16x32_bf16 v[70:73], v[142:145], v[204:207], v[70:73]
	v_mfma_f32_16x16x32_bf16 v[118:121], v[146:149], v[162:165], v[118:121]
	v_mfma_f32_16x16x32_bf16 v[114:117], v[154:157], v[162:165], v[114:117]
	v_mfma_f32_16x16x32_bf16 v[90:93], v[146:149], v[170:173], v[90:93]
	v_mfma_f32_16x16x32_bf16 v[82:85], v[154:157], v[170:173], v[82:85]
	v_mfma_f32_16x16x32_bf16 v[74:77], v[146:149], v[192:195], v[74:77]
	v_mfma_f32_16x16x32_bf16 v[66:69], v[154:157], v[192:195], v[66:69]
	v_mfma_f32_16x16x32_bf16 v[62:65], v[146:149], v[200:203], v[62:65]
	v_mfma_f32_16x16x32_bf16 v[58:61], v[154:157], v[200:203], v[58:61]
	v_mfma_f32_16x16x32_bf16 v[118:121], v[150:153], v[166:169], v[118:121]
	v_mfma_f32_16x16x32_bf16 v[114:117], v[158:161], v[166:169], v[114:117]
	v_mfma_f32_16x16x32_bf16 v[90:93], v[150:153], v[188:191], v[90:93]
	v_mfma_f32_16x16x32_bf16 v[82:85], v[158:161], v[188:191], v[82:85]
	v_mfma_f32_16x16x32_bf16 v[74:77], v[150:153], v[196:199], v[74:77]
	v_mfma_f32_16x16x32_bf16 v[66:69], v[158:161], v[196:199], v[66:69]
	v_mfma_f32_16x16x32_bf16 v[62:65], v[150:153], v[204:207], v[62:65]
	v_mfma_f32_16x16x32_bf16 v[58:61], v[158:161], v[204:207], v[58:61]
	s_barrier
	s_add_i32 s14, s34, s89
	v_lshl_add_u64 v[208:209], s[4:5], 0, v[176:177]
	s_mov_b32 m0, s14
	ds_read_b128 v[162:165], v243 offset:16384
	ds_read_b128 v[166:169], v243 offset:17408
	ds_read_b128 v[170:173], v243 offset:18432
	ds_read_b128 v[188:191], v243 offset:19456
	ds_read_b128 v[192:195], v243 offset:20480
	ds_read_b128 v[196:199], v243 offset:21504
	ds_read_b128 v[200:203], v243 offset:22528
	ds_read_b128 v[204:207], v243 offset:23552
	global_load_lds_dwordx4 v[208:209], off
	s_add_i32 m0, s14, 0x2000
	s_add_u32 s14, s4, 0x100000
	v_lshl_add_u64 v[210:211], s[4:5], 0, v[180:181]
	s_addc_u32 s15, s5, 0
	s_add_i32 s16, s35, s89
	global_load_lds_dwordx4 v[210:211], off
	v_lshl_add_u64 v[212:213], s[14:15], 0, v[176:177]
	s_mov_b32 m0, s16
	v_lshl_add_u64 v[214:215], s[6:7], 0, v[178:179]
	global_load_lds_dwordx4 v[212:213], off
	v_lshl_add_u64 v[212:213], s[14:15], 0, v[180:181]
	s_add_i32 m0, s16, 0x2000
	s_nop 0
	global_load_lds_dwordx4 v[212:213], off
	v_lshl_add_u64 v[212:213], s[6:7], 0, v[174:175]
	s_mov_b32 m0, s73
	s_nop 0
	global_load_lds_dwordx4 v[212:213], off
	s_mov_b32 m0, s90
	s_nop 0
	global_load_lds_dwordx4 v[214:215], off
	s_waitcnt vmcnt(8)
	s_waitcnt lgkmcnt(0)
	s_barrier
; #define PG8_STAGE(bufoff, gbase, voff) do { _Pragma("unroll") for (int _i = 0; _i < 2; ++_i) \
;         __builtin_amdgcn_global_load_lds((const unsigned*)((const char*)(gbase) + (voff)[_i]), (LAS unsigned*)(lds + (bufoff) + ldsw + _i * 8192), 16, 0, 0); } while (0)
; #define PG8_LDA(dst, b, h) do { _Pragma("unroll") for (int m = 0; m < 4; ++m) _Pragma("unroll") for (int k = 0; k < 2; ++k) dst[m][k] = *(const LAS bf16x8*)(lds + PG8_SA(b, h) + aoff + m * 2048 + k * 1024); } while (0)
; #define PG8_LDB(dst, b, h) do { _Pragma("unroll") for (int n = 0; n < 2; ++n) _Pragma("unroll") for (int k = 0; k < 2; ++k) dst[n][k] = *(const LAS bf16x8*)(lds + PG8_SB(b, h) + boff + n * 2048 + k * 1024); } while (0)
; #define PG8_WAIT_V(n) asm volatile("s_waitcnt vmcnt(" #n ")" ::: "memory")
; #define PG8_WAIT_L(n) asm volatile("s_waitcnt lgkmcnt(" #n ")" ::: "memory")
; #define PG8_BAR __builtin_amdgcn_s_barrier()
; #define PG8_SCHED __builtin_amdgcn_sched_barrier(0)
; template <class Epi, class Geom, class Sched, bool ALIGN_EPI, bool I8 = false>
; __device__ __forceinline__ void gemm_phase(LAS unsigned char* lds, const Gemm g, const Sched& S, const Epi& E) {
;     ...
;             PG8_WAIT_V(8); PG8_WAIT_L(0); PG8_BAR; PG8_MMA(1, 0, At, B0); PG8_MMA(1, 1, At, B1); PG8_BAR; PG8_SCHED;
;             PG8_LDB(B0, 1, 0); PG8_LDB(B1, 1, 1); PG8_SCHED; PG8_LDA(At, 1, 0); PG8_STAGE(PG8_SA(0, 1), a2 + hsA, voffA);
;             PG8_WAIT_V(8); PG8_WAIT_L(0); PG8_BAR; PG8_MMA(0, 0, At, B0); PG8_MMA(0, 1, At, B1); PG8_BAR; PG8_SCHED;
	v_mfma_f32_16x16x32_bf16 v[54:57], v[106:109], v[162:165], v[54:57]
	v_mfma_f32_16x16x32_bf16 v[50:53], v[138:141], v[162:165], v[50:53]
	v_mfma_f32_16x16x32_bf16 v[46:49], v[106:109], v[170:173], v[46:49]
	v_mfma_f32_16x16x32_bf16 v[38:41], v[138:141], v[170:173], v[38:41]
	v_mfma_f32_16x16x32_bf16 v[30:33], v[106:109], v[192:195], v[30:33]
	v_mfma_f32_16x16x32_bf16 v[18:21], v[138:141], v[192:195], v[18:21]
	v_mfma_f32_16x16x32_bf16 v[106:109], v[106:109], v[200:203], v[134:137]
	v_mfma_f32_16x16x32_bf16 v[54:57], v[110:113], v[166:169], v[54:57]
	v_mfma_f32_16x16x32_bf16 v[50:53], v[142:145], v[166:169], v[50:53]
	v_mfma_f32_16x16x32_bf16 v[46:49], v[110:113], v[188:191], v[46:49]
	v_mfma_f32_16x16x32_bf16 v[38:41], v[142:145], v[188:191], v[38:41]
	v_mfma_f32_16x16x32_bf16 v[30:33], v[110:113], v[196:199], v[30:33]
	v_mfma_f32_16x16x32_bf16 v[18:21], v[142:145], v[196:199], v[18:21]
	v_mfma_f32_16x16x32_bf16 v[106:109], v[110:113], v[204:207], v[106:109]
	v_mfma_f32_16x16x32_bf16 v[110:113], v[138:141], v[200:203], v[130:133]
	v_mfma_f32_16x16x32_bf16 v[110:113], v[142:145], v[204:207], v[110:113]
	v_mfma_f32_16x16x32_bf16 v[42:45], v[146:149], v[162:165], v[42:45]
	v_mfma_f32_16x16x32_bf16 v[34:37], v[154:157], v[162:165], v[34:37]
	v_mfma_f32_16x16x32_bf16 v[26:29], v[146:149], v[170:173], v[26:29]
	v_mfma_f32_16x16x32_bf16 v[22:25], v[154:157], v[170:173], v[22:25]
	v_mfma_f32_16x16x32_bf16 v[14:17], v[146:149], v[192:195], v[14:17]
	v_mfma_f32_16x16x32_bf16 v[10:13], v[154:157], v[192:195], v[10:13]
	v_mfma_f32_16x16x32_bf16 v[6:9], v[146:149], v[200:203], v[6:9]
	v_mfma_f32_16x16x32_bf16 v[2:5], v[154:157], v[200:203], v[2:5]
	v_mfma_f32_16x16x32_bf16 v[42:45], v[150:153], v[166:169], v[42:45]
	v_mfma_f32_16x16x32_bf16 v[34:37], v[158:161], v[166:169], v[34:37]
	v_mfma_f32_16x16x32_bf16 v[26:29], v[150:153], v[188:191], v[26:29]
	v_mfma_f32_16x16x32_bf16 v[22:25], v[158:161], v[188:191], v[22:25]
	v_mfma_f32_16x16x32_bf16 v[14:17], v[150:153], v[196:199], v[14:17]
	v_mfma_f32_16x16x32_bf16 v[10:13], v[158:161], v[196:199], v[10:13]
	v_mfma_f32_16x16x32_bf16 v[6:9], v[150:153], v[204:207], v[6:9]
	v_mfma_f32_16x16x32_bf16 v[2:5], v[158:161], v[204:207], v[2:5]
	s_barrier
	s_add_i32 s14, 0, 0x18000
	s_add_i32 s15, 0, 0x1c000
	v_add_u32_e32 v142, s14, v240
	v_add_u32_e32 v158, s15, v240
	ds_read_b128 v[130:133], v142
	ds_read_b128 v[134:137], v142 offset:1024
	ds_read_b128 v[138:141], v142 offset:2048
	ds_read_b128 v[142:145], v142 offset:3072
	ds_read_b128 v[146:149], v158
	ds_read_b128 v[150:153], v158 offset:1024
	ds_read_b128 v[154:157], v158 offset:2048
	ds_read_b128 v[158:161], v158 offset:3072
	s_add_u32 s6, s6, 0x100000
	s_addc_u32 s7, s7, 0
	s_mov_b32 m0, s91
	v_lshl_add_u64 v[216:217], s[6:7], 0, v[174:175]
	ds_read_b128 v[162:165], v243 offset:32768
	ds_read_b128 v[166:169], v243 offset:33792
	ds_read_b128 v[170:173], v243 offset:34816
	ds_read_b128 v[188:191], v243 offset:35840
	ds_read_b128 v[192:195], v243 offset:36864
	ds_read_b128 v[196:199], v243 offset:37888
	ds_read_b128 v[200:203], v243 offset:38912
	ds_read_b128 v[204:207], v243 offset:39936
	global_load_lds_dwordx4 v[216:217], off
	v_lshl_add_u64 v[216:217], s[6:7], 0, v[178:179]
	s_mov_b32 m0, s92
	s_nop 0
	global_load_lds_dwordx4 v[216:217], off
	s_waitcnt vmcnt(8)
	s_waitcnt lgkmcnt(0)
	s_barrier
	v_mfma_f32_16x16x32_bf16 v[122:125], v[130:133], v[162:165], v[122:125]
	v_mfma_f32_16x16x32_bf16 v[126:129], v[138:141], v[162:165], v[126:129]
	v_mfma_f32_16x16x32_bf16 v[102:105], v[130:133], v[170:173], v[102:105]
	v_mfma_f32_16x16x32_bf16 v[98:101], v[138:141], v[170:173], v[98:101]
	v_mfma_f32_16x16x32_bf16 v[94:97], v[130:133], v[192:195], v[94:97]
	v_mfma_f32_16x16x32_bf16 v[86:89], v[138:141], v[192:195], v[86:89]
	v_mfma_f32_16x16x32_bf16 v[78:81], v[130:133], v[200:203], v[78:81]
	v_mfma_f32_16x16x32_bf16 v[70:73], v[138:141], v[200:203], v[70:73]
	v_mfma_f32_16x16x32_bf16 v[122:125], v[134:137], v[166:169], v[122:125]
	v_mfma_f32_16x16x32_bf16 v[126:129], v[142:145], v[166:169], v[126:129]
	v_mfma_f32_16x16x32_bf16 v[102:105], v[134:137], v[188:191], v[102:105]
	v_mfma_f32_16x16x32_bf16 v[98:101], v[142:145], v[188:191], v[98:101]
	v_mfma_f32_16x16x32_bf16 v[94:97], v[134:137], v[196:199], v[94:97]
	v_mfma_f32_16x16x32_bf16 v[86:89], v[142:145], v[196:199], v[86:89]
	v_mfma_f32_16x16x32_bf16 v[78:81], v[134:137], v[204:207], v[78:81]
	v_mfma_f32_16x16x32_bf16 v[70:73], v[142:145], v[204:207], v[70:73]
	v_mfma_f32_16x16x32_bf16 v[118:121], v[146:149], v[162:165], v[118:121]
	v_mfma_f32_16x16x32_bf16 v[114:117], v[154:157], v[162:165], v[114:117]
	v_mfma_f32_16x16x32_bf16 v[90:93], v[146:149], v[170:173], v[90:93]
	v_mfma_f32_16x16x32_bf16 v[82:85], v[154:157], v[170:173], v[82:85]
	v_mfma_f32_16x16x32_bf16 v[74:77], v[146:149], v[192:195], v[74:77]
	v_mfma_f32_16x16x32_bf16 v[66:69], v[154:157], v[192:195], v[66:69]
	v_mfma_f32_16x16x32_bf16 v[62:65], v[146:149], v[200:203], v[62:65]
	v_mfma_f32_16x16x32_bf16 v[58:61], v[154:157], v[200:203], v[58:61]
	v_mfma_f32_16x16x32_bf16 v[118:121], v[150:153], v[166:169], v[118:121]
	v_mfma_f32_16x16x32_bf16 v[114:117], v[158:161], v[166:169], v[114:117]
	v_mfma_f32_16x16x32_bf16 v[90:93], v[150:153], v[188:191], v[90:93]
	v_mfma_f32_16x16x32_bf16 v[82:85], v[158:161], v[188:191], v[82:85]
	v_mfma_f32_16x16x32_bf16 v[74:77], v[150:153], v[196:199], v[74:77]
	v_mfma_f32_16x16x32_bf16 v[66:69], v[158:161], v[196:199], v[66:69]
	v_mfma_f32_16x16x32_bf16 v[62:65], v[150:153], v[204:207], v[62:65]
	v_mfma_f32_16x16x32_bf16 v[58:61], v[158:161], v[204:207], v[58:61]
	s_barrier
; #define PG8_STAGE(bufoff, gbase, voff) do { _Pragma("unroll") for (int _i = 0; _i < 2; ++_i) \
;         __builtin_amdgcn_global_load_lds((const unsigned*)((const char*)(gbase) + (voff)[_i]), (LAS unsigned*)(lds + (bufoff) + ldsw + _i * 8192), 16, 0, 0); } while (0)
; #define PG8_LDA(dst, b, h) do { _Pragma("unroll") for (int m = 0; m < 4; ++m) _Pragma("unroll") for (int k = 0; k < 2; ++k) dst[m][k] = *(const LAS bf16x8*)(lds + PG8_SA(b, h) + aoff + m * 2048 + k * 1024); } while (0)
; #define PG8_WAIT_V(n) asm volatile("s_waitcnt vmcnt(" #n ")" ::: "memory")
; #define PG8_WAIT_L(n) asm volatile("s_waitcnt lgkmcnt(" #n ")" ::: "memory")
; #define PG8_BAR __builtin_amdgcn_s_barrier()
; #define PG8_SCHED __builtin_amdgcn_sched_barrier(0)
; template <class Epi, class Geom, class Sched, bool ALIGN_EPI, bool I8 = false>
; __device__ __forceinline__ void gemm_phase(LAS unsigned char* lds, const Gemm g, const Sched& S, const Epi& E) {
;     ...
;             PG8_LDA(At, 1, 1); PG8_STAGE(PG8_SB(1, 0), b3, voffB); PG8_STAGE(PG8_SB(1, 1), b3 + hsB, voffB); PG8_STAGE(PG8_SA(1, 0), a3, voffA);
;             PG8_WAIT_V(8); PG8_WAIT_L(0); PG8_BAR; PG8_MMA(1, 0, At, B0); PG8_MMA(1, 1, At, B1); PG8_BAR; PG8_SCHED;
;         }
	s_add_i32 s6, s14, s89
	v_lshl_add_u64 v[208:209], v[208:209], 0, s[28:29]
	s_mov_b32 m0, s6
	ds_read_b128 v[162:165], v243 offset:49152
	ds_read_b128 v[166:169], v243 offset:50176
	ds_read_b128 v[170:173], v243 offset:51200
	ds_read_b128 v[188:191], v243 offset:52224
	ds_read_b128 v[192:195], v243 offset:53248
	ds_read_b128 v[196:199], v243 offset:54272
	ds_read_b128 v[200:203], v243 offset:55296
	ds_read_b128 v[204:207], v243 offset:56320
	global_load_lds_dwordx4 v[208:209], off
	s_add_i32 m0, s6, 0x2000
	s_add_u32 s4, s4, 0x100080
	v_lshl_add_u64 v[208:209], v[210:211], 0, s[28:29]
	s_addc_u32 s5, s5, 0
	s_add_i32 s6, s15, s89
	global_load_lds_dwordx4 v[208:209], off
	v_lshl_add_u64 v[208:209], s[4:5], 0, v[176:177]
	s_mov_b32 m0, s6
	s_nop 0
	global_load_lds_dwordx4 v[208:209], off
	v_lshl_add_u64 v[208:209], s[4:5], 0, v[180:181]
	s_add_i32 m0, s6, 0x2000
	s_nop 0
	global_load_lds_dwordx4 v[208:209], off
	v_lshl_add_u64 v[208:209], v[212:213], 0, s[28:29]
	s_mov_b32 m0, s96
	s_nop 0
	global_load_lds_dwordx4 v[208:209], off
	v_lshl_add_u64 v[208:209], v[214:215], 0, s[28:29]
	s_mov_b32 m0, s97
	s_nop 0
	global_load_lds_dwordx4 v[208:209], off
	s_waitcnt vmcnt(8)
	s_waitcnt lgkmcnt(0)
	s_barrier
	v_mfma_f32_16x16x32_bf16 v[54:57], v[130:133], v[162:165], v[54:57]
	v_mfma_f32_16x16x32_bf16 v[46:49], v[130:133], v[170:173], v[46:49]
	v_mfma_f32_16x16x32_bf16 v[30:33], v[130:133], v[192:195], v[30:33]
	v_mfma_f32_16x16x32_bf16 v[106:109], v[130:133], v[200:203], v[106:109]
	v_mfma_f32_16x16x32_bf16 v[54:57], v[134:137], v[166:169], v[54:57]
	v_mfma_f32_16x16x32_bf16 v[50:53], v[138:141], v[162:165], v[50:53]
	v_mfma_f32_16x16x32_bf16 v[46:49], v[134:137], v[188:191], v[46:49]
	v_mfma_f32_16x16x32_bf16 v[38:41], v[138:141], v[170:173], v[38:41]
	v_mfma_f32_16x16x32_bf16 v[30:33], v[134:137], v[196:199], v[30:33]
	v_mfma_f32_16x16x32_bf16 v[18:21], v[138:141], v[192:195], v[18:21]
	v_mfma_f32_16x16x32_bf16 v[134:137], v[134:137], v[204:207], v[106:109]
	v_mfma_f32_16x16x32_bf16 v[106:109], v[138:141], v[200:203], v[110:113]
	v_mfma_f32_16x16x32_bf16 v[50:53], v[142:145], v[166:169], v[50:53]
	v_mfma_f32_16x16x32_bf16 v[38:41], v[142:145], v[188:191], v[38:41]
	v_mfma_f32_16x16x32_bf16 v[18:21], v[142:145], v[196:199], v[18:21]
	v_mfma_f32_16x16x32_bf16 v[130:133], v[142:145], v[204:207], v[106:109]
	v_mfma_f32_16x16x32_bf16 v[42:45], v[146:149], v[162:165], v[42:45]
	v_mfma_f32_16x16x32_bf16 v[34:37], v[154:157], v[162:165], v[34:37]
	v_mfma_f32_16x16x32_bf16 v[26:29], v[146:149], v[170:173], v[26:29]
	v_mfma_f32_16x16x32_bf16 v[22:25], v[154:157], v[170:173], v[22:25]
	v_mfma_f32_16x16x32_bf16 v[14:17], v[146:149], v[192:195], v[14:17]
	v_mfma_f32_16x16x32_bf16 v[10:13], v[154:157], v[192:195], v[10:13]
	v_mfma_f32_16x16x32_bf16 v[6:9], v[146:149], v[200:203], v[6:9]
	v_mfma_f32_16x16x32_bf16 v[2:5], v[154:157], v[200:203], v[2:5]
	v_mfma_f32_16x16x32_bf16 v[42:45], v[150:153], v[166:169], v[42:45]
	v_mfma_f32_16x16x32_bf16 v[34:37], v[158:161], v[166:169], v[34:37]
	v_mfma_f32_16x16x32_bf16 v[26:29], v[150:153], v[188:191], v[26:29]
	v_mfma_f32_16x16x32_bf16 v[22:25], v[158:161], v[188:191], v[22:25]
	v_mfma_f32_16x16x32_bf16 v[14:17], v[150:153], v[196:199], v[14:17]
	v_mfma_f32_16x16x32_bf16 v[10:13], v[158:161], v[196:199], v[10:13]
	v_mfma_f32_16x16x32_bf16 v[6:9], v[150:153], v[204:207], v[6:9]
	v_mfma_f32_16x16x32_bf16 v[2:5], v[158:161], v[204:207], v[2:5]
	s_barrier
	s_add_i32 s13, s13, 2
	s_add_u32 s0, s0, 0x100
	s_addc_u32 s1, s1, 0
	s_add_u32 s11, s11, 0x100
	s_addc_u32 s12, s12, 0
	s_cmp_gt_u32 s13, 61
	s_cbranch_scc0 .LBB0_194
	s_and_b64 vcc, exec, s[84:85]
	s_cbranch_vccz .LBB0_197
	s_barrier

; #define PG8_STAGE(bufoff, gbase, voff) do { _Pragma("unroll") for (int _i = 0; _i < 2; ++_i) \
;         __builtin_amdgcn_global_load_lds((const unsigned*)((const char*)(gbase) + (voff)[_i]), (LAS unsigned*)(lds + (bufoff) + ldsw + _i * 8192), 16, 0, 0); } while (0)
; #define PG8_LDA(dst, b, h) do { _Pragma("unroll") for (int m = 0; m < 4; ++m) _Pragma("unroll") for (int k = 0; k < 2; ++k) dst[m][k] = *(const LAS bf16x8*)(lds + PG8_SA(b, h) + aoff + m * 2048 + k * 1024); } while (0)
; #define PG8_LDB(dst, b, h) do { _Pragma("unroll") for (int n = 0; n < 2; ++n) _Pragma("unroll") for (int k = 0; k < 2; ++k) dst[n][k] = *(const LAS bf16x8*)(lds + PG8_SB(b, h) + boff + n * 2048 + k * 1024); } while (0)
; #define PG8_WAIT_V(n) asm volatile("s_waitcnt vmcnt(" #n ")" ::: "memory")
; #define PG8_WAIT_L(n) asm volatile("s_waitcnt lgkmcnt(" #n ")" ::: "memory")
; #define PG8_BAR __builtin_amdgcn_s_barrier()
; #define PG8_SCHED __builtin_amdgcn_sched_barrier(0)
; template <class Epi, class Geom, class Sched, bool ALIGN_EPI, bool I8 = false>
; __device__ __forceinline__ void gemm_phase(LAS unsigned char* lds, const Gemm g, const Sched& S, const Epi& E) {
;     ...
;             PG8_LDB(B0, 0, 0); PG8_LDB(B1, 0, 1); PG8_SCHED; PG8_LDA(At, 0, 0); PG8_STAGE(PG8_SA(1, 1), a1 + hsA, voffA);
;             PG8_WAIT_V(8); PG8_WAIT_L(0); PG8_BAR; PG8_MMA(0, 0, At, B0); PG8_MMA(0, 1, At, B1); PG8_BAR; PG8_SCHED;
;             PG8_LDA(At, 0, 1); PG8_STAGE(PG8_SB(0, 0), b2, voffB); PG8_STAGE(PG8_SB(0, 1), b2 + hsB, voffB); PG8_STAGE(PG8_SA(0, 0), a2, voffA);
;             PG8_WAIT_V(8); PG8_WAIT_L(0); PG8_BAR; PG8_MMA(1, 0, At, B0); PG8_MMA(1, 1, At, B1); PG8_BAR; PG8_SCHED;
.LBB0_1860:
	s_add_u32 s35, s26, s34
	s_addc_u32 s40, s27, 0
	s_add_u32 s38, s35, 0x100
	s_addc_u32 s39, s40, 0
	s_and_b64 s[36:37], s[30:31], exec
	s_cselect_b32 s37, s1, s39
	s_cselect_b32 s36, s21, s38
	s_add_u32 s34, s2, s34
	s_addc_u32 s38, s3, 0
	s_add_u32 s34, s34, 0x100
	s_addc_u32 s38, s38, 0
	s_and_b64 s[30:31], s[30:31], exec
	s_cselect_b32 s39, s19, s38
	s_cselect_b32 s38, s63, s34
	s_add_u32 s42, s35, 0x80080
	ds_read_b128 v[50:53], v203
	ds_read_b128 v[54:57], v203 offset:1024
	ds_read_b128 v[58:61], v203 offset:2048
	ds_read_b128 v[122:125], v203 offset:3072
	ds_read_b128 v[126:129], v204
	ds_read_b128 v[130:133], v204 offset:1024
	ds_read_b128 v[168:171], v204 offset:2048
	ds_read_b128 v[172:175], v204 offset:3072
	s_addc_u32 s43, s40, 0
	s_add_i32 s73, s61, s50
	s_add_i32 m0, s53, 0xc000
	s_add_i32 s74, s53, 0xe000
	s_add_i32 s70, s73, 0x2000
	s_add_u32 s40, s38, 0x10000
	s_addc_u32 s41, s39, 0
	s_add_i32 s72, s62, s50
	s_add_i32 s71, s72, 0x2000
	s_add_i32 s69, 0, 0x18000
	s_add_i32 s68, 0, 0x1c000
	s_add_u32 s34, s36, 0x80000
	s_addc_u32 s35, s37, 0
	s_add_i32 s67, s69, s50
	s_add_i32 s65, s67, 0x2000
	s_add_u32 s30, s38, 0x10080
	s_addc_u32 s31, s39, 0
	s_add_i32 s66, s68, s50
	s_add_i32 s64, s66, 0x2000
	v_lshl_add_u64 v[216:217], s[42:43], 0, v[160:161]
	ds_read_b128 v[176:179], v205
	ds_read_b128 v[180:183], v205 offset:1024
	ds_read_b128 v[184:187], v205 offset:2048
	ds_read_b128 v[188:191], v205 offset:3072
	ds_read_b128 v[192:195], v205 offset:4096
	ds_read_b128 v[196:199], v205 offset:5120
	ds_read_b128 v[208:211], v205 offset:6144
	ds_read_b128 v[212:215], v205 offset:7168
	global_load_lds_dwordx4 v[216:217], off
	v_lshl_add_u64 v[216:217], s[42:43], 0, v[156:157]
	s_mov_b32 m0, s74
	s_nop 0
	global_load_lds_dwordx4 v[216:217], off
	s_waitcnt vmcnt(8)
	s_waitcnt lgkmcnt(0)
	s_barrier
	v_mfma_f32_16x16x32_bf16 v[150:153], v[50:53], v[176:179], v[150:153]
	v_mfma_f32_16x16x32_bf16 v[74:77], v[58:61], v[176:179], v[74:77]
	v_mfma_f32_16x16x32_bf16 v[142:145], v[50:53], v[184:187], v[142:145]
	v_mfma_f32_16x16x32_bf16 v[66:69], v[58:61], v[184:187], v[66:69]
	v_mfma_f32_16x16x32_bf16 v[134:137], v[50:53], v[192:195], v[134:137]
	v_mfma_f32_16x16x32_bf16 v[46:49], v[58:61], v[192:195], v[46:49]
	v_mfma_f32_16x16x32_bf16 v[114:117], v[50:53], v[208:211], v[114:117]
	v_mfma_f32_16x16x32_bf16 v[38:41], v[58:61], v[208:211], v[38:41]
	v_mfma_f32_16x16x32_bf16 v[150:153], v[54:57], v[180:183], v[150:153]
	v_mfma_f32_16x16x32_bf16 v[74:77], v[122:125], v[180:183], v[74:77]
	v_mfma_f32_16x16x32_bf16 v[142:145], v[54:57], v[188:191], v[142:145]
	v_mfma_f32_16x16x32_bf16 v[66:69], v[122:125], v[188:191], v[66:69]
	v_mfma_f32_16x16x32_bf16 v[134:137], v[54:57], v[196:199], v[134:137]
	v_mfma_f32_16x16x32_bf16 v[46:49], v[122:125], v[196:199], v[46:49]
	v_mfma_f32_16x16x32_bf16 v[114:117], v[54:57], v[212:215], v[114:117]
	v_mfma_f32_16x16x32_bf16 v[38:41], v[122:125], v[212:215], v[38:41]
	v_mfma_f32_16x16x32_bf16 v[146:149], v[126:129], v[176:179], v[146:149]
	v_mfma_f32_16x16x32_bf16 v[70:73], v[168:171], v[176:179], v[70:73]
	v_mfma_f32_16x16x32_bf16 v[138:141], v[126:129], v[184:187], v[138:141]
	v_mfma_f32_16x16x32_bf16 v[62:65], v[168:171], v[184:187], v[62:65]
	v_mfma_f32_16x16x32_bf16 v[118:121], v[126:129], v[192:195], v[118:121]
	v_mfma_f32_16x16x32_bf16 v[42:45], v[168:171], v[192:195], v[42:45]
	v_mfma_f32_16x16x32_bf16 v[110:113], v[126:129], v[208:211], v[110:113]
	v_mfma_f32_16x16x32_bf16 v[34:37], v[168:171], v[208:211], v[34:37]
	v_mfma_f32_16x16x32_bf16 v[146:149], v[130:133], v[180:183], v[146:149]
	v_mfma_f32_16x16x32_bf16 v[70:73], v[172:175], v[180:183], v[70:73]
	v_mfma_f32_16x16x32_bf16 v[138:141], v[130:133], v[188:191], v[138:141]
	v_mfma_f32_16x16x32_bf16 v[62:65], v[172:175], v[188:191], v[62:65]
	v_mfma_f32_16x16x32_bf16 v[118:121], v[130:133], v[196:199], v[118:121]
	v_mfma_f32_16x16x32_bf16 v[42:45], v[172:175], v[196:199], v[42:45]
	v_mfma_f32_16x16x32_bf16 v[110:113], v[130:133], v[212:215], v[110:113]
	v_mfma_f32_16x16x32_bf16 v[34:37], v[172:175], v[212:215], v[34:37]
	s_barrier
	s_mov_b32 m0, s73
	v_lshl_add_u64 v[216:217], s[38:39], 0, v[158:159]
	ds_read_b128 v[176:179], v205 offset:16384
	ds_read_b128 v[180:183], v205 offset:17408
	ds_read_b128 v[184:187], v205 offset:18432
	ds_read_b128 v[188:191], v205 offset:19456
	ds_read_b128 v[192:195], v205 offset:20480
	ds_read_b128 v[196:199], v205 offset:21504
	ds_read_b128 v[208:211], v205 offset:22528
	ds_read_b128 v[212:215], v205 offset:23552
	global_load_lds_dwordx4 v[216:217], off
	v_lshl_add_u64 v[218:219], s[38:39], 0, v[154:155]
	s_mov_b32 m0, s70
	v_lshl_add_u64 v[220:221], s[40:41], 0, v[158:159]
	global_load_lds_dwordx4 v[218:219], off
	s_mov_b32 m0, s72
	v_lshl_add_u64 v[222:223], s[36:37], 0, v[156:157]
	global_load_lds_dwordx4 v[220:221], off
	v_lshl_add_u64 v[220:221], s[40:41], 0, v[154:155]
	s_mov_b32 m0, s71
	s_nop 0
	global_load_lds_dwordx4 v[220:221], off
	v_lshl_add_u64 v[220:221], s[36:37], 0, v[160:161]
	s_mov_b32 m0, s53
	s_nop 0
	global_load_lds_dwordx4 v[220:221], off
	s_mov_b32 m0, s54
	s_nop 0
	global_load_lds_dwordx4 v[222:223], off
	s_waitcnt vmcnt(8)
	s_waitcnt lgkmcnt(0)
	s_barrier
; #define PG8_STAGE(bufoff, gbase, voff) do { _Pragma("unroll") for (int _i = 0; _i < 2; ++_i) \
;         __builtin_amdgcn_global_load_lds((const unsigned*)((const char*)(gbase) + (voff)[_i]), (LAS unsigned*)(lds + (bufoff) + ldsw + _i * 8192), 16, 0, 0); } while (0)
; #define PG8_LDA(dst, b, h) do { _Pragma("unroll") for (int m = 0; m < 4; ++m) _Pragma("unroll") for (int k = 0; k < 2; ++k) dst[m][k] = *(const LAS bf16x8*)(lds + PG8_SA(b, h) + aoff + m * 2048 + k * 1024); } while (0)
; #define PG8_LDB(dst, b, h) do { _Pragma("unroll") for (int n = 0; n < 2; ++n) _Pragma("unroll") for (int k = 0; k < 2; ++k) dst[n][k] = *(const LAS bf16x8*)(lds + PG8_SB(b, h) + boff + n * 2048 + k * 1024); } while (0)
; #define PG8_WAIT_V(n) asm volatile("s_waitcnt vmcnt(" #n ")" ::: "memory")
; #define PG8_WAIT_L(n) asm volatile("s_waitcnt lgkmcnt(" #n ")" ::: "memory")
; #define PG8_BAR __builtin_amdgcn_s_barrier()
; #define PG8_SCHED __builtin_amdgcn_sched_barrier(0)
; template <class Epi, class Geom, class Sched, bool ALIGN_EPI, bool I8 = false>
; __device__ __forceinline__ void gemm_phase(LAS unsigned char* lds, const Gemm g, const Sched& S, const Epi& E) {
;     ...
;             PG8_WAIT_V(8); PG8_WAIT_L(0); PG8_BAR; PG8_MMA(1, 0, At, B0); PG8_MMA(1, 1, At, B1); PG8_BAR; PG8_SCHED;
;             PG8_LDB(B0, 1, 0); PG8_LDB(B1, 1, 1); PG8_SCHED; PG8_LDA(At, 1, 0); PG8_STAGE(PG8_SA(0, 1), a2 + hsA, voffA);
;             PG8_WAIT_V(8); PG8_WAIT_L(0); PG8_BAR; PG8_MMA(0, 0, At, B0); PG8_MMA(0, 1, At, B1); PG8_BAR; PG8_SCHED;
	v_mfma_f32_16x16x32_bf16 v[106:109], v[50:53], v[176:179], v[106:109]
	v_mfma_f32_16x16x32_bf16 v[30:33], v[58:61], v[176:179], v[30:33]
	v_mfma_f32_16x16x32_bf16 v[98:101], v[50:53], v[184:187], v[98:101]
	v_mfma_f32_16x16x32_bf16 v[22:25], v[58:61], v[184:187], v[22:25]
	v_mfma_f32_16x16x32_bf16 v[90:93], v[50:53], v[192:195], v[90:93]
	v_mfma_f32_16x16x32_bf16 v[14:17], v[58:61], v[192:195], v[14:17]
	v_mfma_f32_16x16x32_bf16 v[6:9], v[58:61], v[208:211], v[6:9]
	v_mfma_f32_16x16x32_bf16 v[106:109], v[54:57], v[180:183], v[106:109]
	v_mfma_f32_16x16x32_bf16 v[30:33], v[122:125], v[180:183], v[30:33]
	v_mfma_f32_16x16x32_bf16 v[98:101], v[54:57], v[188:191], v[98:101]
	v_mfma_f32_16x16x32_bf16 v[22:25], v[122:125], v[188:191], v[22:25]
	v_mfma_f32_16x16x32_bf16 v[90:93], v[54:57], v[196:199], v[90:93]
	v_mfma_f32_16x16x32_bf16 v[14:17], v[122:125], v[196:199], v[14:17]
	v_mfma_f32_16x16x32_bf16 v[50:53], v[50:53], v[208:211], v[82:85]
	v_mfma_f32_16x16x32_bf16 v[6:9], v[122:125], v[212:215], v[6:9]
	v_mfma_f32_16x16x32_bf16 v[50:53], v[54:57], v[212:215], v[50:53]
	v_mfma_f32_16x16x32_bf16 v[26:29], v[168:171], v[176:179], v[26:29]
	v_mfma_f32_16x16x32_bf16 v[18:21], v[168:171], v[184:187], v[18:21]
	v_mfma_f32_16x16x32_bf16 v[82:85], v[126:129], v[192:195], v[86:89]
	v_mfma_f32_16x16x32_bf16 v[10:13], v[168:171], v[192:195], v[10:13]
	v_mfma_f32_16x16x32_bf16 v[78:81], v[126:129], v[208:211], v[78:81]
	v_mfma_f32_16x16x32_bf16 v[2:5], v[168:171], v[208:211], v[2:5]
	v_mfma_f32_16x16x32_bf16 v[54:57], v[126:129], v[176:179], v[102:105]
	v_mfma_f32_16x16x32_bf16 v[26:29], v[172:175], v[180:183], v[26:29]
	v_mfma_f32_16x16x32_bf16 v[58:61], v[126:129], v[184:187], v[94:97]
	v_mfma_f32_16x16x32_bf16 v[18:21], v[172:175], v[188:191], v[18:21]
	v_mfma_f32_16x16x32_bf16 v[86:89], v[130:133], v[196:199], v[82:85]
	v_mfma_f32_16x16x32_bf16 v[10:13], v[172:175], v[196:199], v[10:13]
	v_mfma_f32_16x16x32_bf16 v[78:81], v[130:133], v[212:215], v[78:81]
	v_mfma_f32_16x16x32_bf16 v[2:5], v[172:175], v[212:215], v[2:5]
	v_mfma_f32_16x16x32_bf16 v[54:57], v[130:133], v[180:183], v[54:57]
	v_mfma_f32_16x16x32_bf16 v[58:61], v[130:133], v[188:191], v[58:61]
	s_barrier
	v_add_u32_e32 v122, s69, v200
	v_add_u32_e32 v162, s68, v200
	ds_read_b128 v[82:85], v122
	ds_read_b128 v[94:97], v122 offset:1024
	ds_read_b128 v[102:105], v122 offset:2048
	ds_read_b128 v[122:125], v122 offset:3072
	ds_read_b128 v[126:129], v162
	ds_read_b128 v[130:133], v162 offset:1024
	ds_read_b128 v[168:171], v162 offset:2048
	ds_read_b128 v[172:175], v162 offset:3072
	s_mov_b32 m0, s55
	v_lshl_add_u64 v[224:225], s[34:35], 0, v[160:161]
	ds_read_b128 v[176:179], v205 offset:32768
	ds_read_b128 v[180:183], v205 offset:33792
	ds_read_b128 v[184:187], v205 offset:34816
	ds_read_b128 v[188:191], v205 offset:35840
	ds_read_b128 v[192:195], v205 offset:36864
	ds_read_b128 v[196:199], v205 offset:37888
	ds_read_b128 v[208:211], v205 offset:38912
	ds_read_b128 v[212:215], v205 offset:39936
	global_load_lds_dwordx4 v[224:225], off
	v_lshl_add_u64 v[224:225], s[34:35], 0, v[156:157]
	s_mov_b32 m0, s56
	s_nop 0
	global_load_lds_dwordx4 v[224:225], off
	s_waitcnt vmcnt(8)
	s_waitcnt lgkmcnt(0)
	s_barrier
	v_mfma_f32_16x16x32_bf16 v[150:153], v[82:85], v[176:179], v[150:153]
	v_mfma_f32_16x16x32_bf16 v[74:77], v[102:105], v[176:179], v[74:77]
	v_mfma_f32_16x16x32_bf16 v[142:145], v[82:85], v[184:187], v[142:145]
	v_mfma_f32_16x16x32_bf16 v[66:69], v[102:105], v[184:187], v[66:69]
	v_mfma_f32_16x16x32_bf16 v[134:137], v[82:85], v[192:195], v[134:137]
	v_mfma_f32_16x16x32_bf16 v[46:49], v[102:105], v[192:195], v[46:49]
	v_mfma_f32_16x16x32_bf16 v[114:117], v[82:85], v[208:211], v[114:117]
	v_mfma_f32_16x16x32_bf16 v[38:41], v[102:105], v[208:211], v[38:41]
	v_mfma_f32_16x16x32_bf16 v[150:153], v[94:97], v[180:183], v[150:153]
	v_mfma_f32_16x16x32_bf16 v[74:77], v[122:125], v[180:183], v[74:77]
	v_mfma_f32_16x16x32_bf16 v[142:145], v[94:97], v[188:191], v[142:145]
	v_mfma_f32_16x16x32_bf16 v[66:69], v[122:125], v[188:191], v[66:69]
	v_mfma_f32_16x16x32_bf16 v[134:137], v[94:97], v[196:199], v[134:137]
	v_mfma_f32_16x16x32_bf16 v[46:49], v[122:125], v[196:199], v[46:49]
	v_mfma_f32_16x16x32_bf16 v[114:117], v[94:97], v[212:215], v[114:117]
	v_mfma_f32_16x16x32_bf16 v[38:41], v[122:125], v[212:215], v[38:41]
	v_mfma_f32_16x16x32_bf16 v[146:149], v[126:129], v[176:179], v[146:149]
	v_mfma_f32_16x16x32_bf16 v[70:73], v[168:171], v[176:179], v[70:73]
	v_mfma_f32_16x16x32_bf16 v[138:141], v[126:129], v[184:187], v[138:141]
	v_mfma_f32_16x16x32_bf16 v[62:65], v[168:171], v[184:187], v[62:65]
	v_mfma_f32_16x16x32_bf16 v[118:121], v[126:129], v[192:195], v[118:121]
	v_mfma_f32_16x16x32_bf16 v[42:45], v[168:171], v[192:195], v[42:45]
	v_mfma_f32_16x16x32_bf16 v[110:113], v[126:129], v[208:211], v[110:113]
	v_mfma_f32_16x16x32_bf16 v[34:37], v[168:171], v[208:211], v[34:37]
	v_mfma_f32_16x16x32_bf16 v[146:149], v[130:133], v[180:183], v[146:149]
	v_mfma_f32_16x16x32_bf16 v[70:73], v[172:175], v[180:183], v[70:73]
	v_mfma_f32_16x16x32_bf16 v[138:141], v[130:133], v[188:191], v[138:141]
	v_mfma_f32_16x16x32_bf16 v[62:65], v[172:175], v[188:191], v[62:65]
	v_mfma_f32_16x16x32_bf16 v[118:121], v[130:133], v[196:199], v[118:121]
	v_mfma_f32_16x16x32_bf16 v[42:45], v[172:175], v[196:199], v[42:45]
	v_mfma_f32_16x16x32_bf16 v[110:113], v[130:133], v[212:215], v[110:113]
	v_mfma_f32_16x16x32_bf16 v[34:37], v[172:175], v[212:215], v[34:37]
	s_barrier
; #define PG8_STAGE(bufoff, gbase, voff) do { _Pragma("unroll") for (int _i = 0; _i < 2; ++_i) \
;         __builtin_amdgcn_global_load_lds((const unsigned*)((const char*)(gbase) + (voff)[_i]), (LAS unsigned*)(lds + (bufoff) + ldsw + _i * 8192), 16, 0, 0); } while (0)
; #define PG8_LDA(dst, b, h) do { _Pragma("unroll") for (int m = 0; m < 4; ++m) _Pragma("unroll") for (int k = 0; k < 2; ++k) dst[m][k] = *(const LAS bf16x8*)(lds + PG8_SA(b, h) + aoff + m * 2048 + k * 1024); } while (0)
; #define PG8_WAIT_V(n) asm volatile("s_waitcnt vmcnt(" #n ")" ::: "memory")
; #define PG8_WAIT_L(n) asm volatile("s_waitcnt lgkmcnt(" #n ")" ::: "memory")
; #define PG8_BAR __builtin_amdgcn_s_barrier()
; #define PG8_SCHED __builtin_amdgcn_sched_barrier(0)
; template <class Epi, class Geom, class Sched, bool ALIGN_EPI, bool I8 = false>
; __device__ __forceinline__ void gemm_phase(LAS unsigned char* lds, const Gemm g, const Sched& S, const Epi& E) {
;     ...
;             PG8_LDA(At, 1, 1); PG8_STAGE(PG8_SB(1, 0), b3, voffB); PG8_STAGE(PG8_SB(1, 1), b3 + hsB, voffB); PG8_STAGE(PG8_SA(1, 0), a3, voffA);
;             PG8_WAIT_V(8); PG8_WAIT_L(0); PG8_BAR; PG8_MMA(1, 0, At, B0); PG8_MMA(1, 1, At, B1); PG8_BAR; PG8_SCHED;
;         }
	s_mov_b32 m0, s67
	v_lshl_add_u64 v[216:217], v[216:217], 0, s[14:15]
	ds_read_b128 v[176:179], v205 offset:49152
	ds_read_b128 v[180:183], v205 offset:50176
	ds_read_b128 v[184:187], v205 offset:51200
	ds_read_b128 v[188:191], v205 offset:52224
	ds_read_b128 v[192:195], v205 offset:53248
	ds_read_b128 v[196:199], v205 offset:54272
	ds_read_b128 v[208:211], v205 offset:55296
	ds_read_b128 v[212:215], v205 offset:56320
	global_load_lds_dwordx4 v[216:217], off
	v_lshl_add_u64 v[216:217], v[218:219], 0, s[14:15]
	s_mov_b32 m0, s65
	s_nop 0
	global_load_lds_dwordx4 v[216:217], off
	v_lshl_add_u64 v[216:217], s[30:31], 0, v[158:159]
	s_mov_b32 m0, s66
	s_nop 0
	global_load_lds_dwordx4 v[216:217], off
	v_lshl_add_u64 v[216:217], s[30:31], 0, v[154:155]
	s_mov_b32 m0, s64
	s_nop 0
	global_load_lds_dwordx4 v[216:217], off
	v_lshl_add_u64 v[216:217], v[220:221], 0, s[14:15]
	s_mov_b32 m0, s58
	s_nop 0
	global_load_lds_dwordx4 v[216:217], off
	v_lshl_add_u64 v[216:217], v[222:223], 0, s[14:15]
	s_mov_b32 m0, s59
	s_nop 0
	global_load_lds_dwordx4 v[216:217], off
	s_waitcnt vmcnt(8)
	s_waitcnt lgkmcnt(0)
	s_barrier
	v_mfma_f32_16x16x32_bf16 v[106:109], v[82:85], v[176:179], v[106:109]
	v_mfma_f32_16x16x32_bf16 v[30:33], v[102:105], v[176:179], v[30:33]
	v_mfma_f32_16x16x32_bf16 v[98:101], v[82:85], v[184:187], v[98:101]
	v_mfma_f32_16x16x32_bf16 v[22:25], v[102:105], v[184:187], v[22:25]
	v_mfma_f32_16x16x32_bf16 v[90:93], v[82:85], v[192:195], v[90:93]
	v_mfma_f32_16x16x32_bf16 v[14:17], v[102:105], v[192:195], v[14:17]
	v_mfma_f32_16x16x32_bf16 v[50:53], v[82:85], v[208:211], v[50:53]
	v_mfma_f32_16x16x32_bf16 v[6:9], v[102:105], v[208:211], v[6:9]
	v_mfma_f32_16x16x32_bf16 v[106:109], v[94:97], v[180:183], v[106:109]
	v_mfma_f32_16x16x32_bf16 v[30:33], v[122:125], v[180:183], v[30:33]
	v_mfma_f32_16x16x32_bf16 v[98:101], v[94:97], v[188:191], v[98:101]
	v_mfma_f32_16x16x32_bf16 v[22:25], v[122:125], v[188:191], v[22:25]
	v_mfma_f32_16x16x32_bf16 v[90:93], v[94:97], v[196:199], v[90:93]
	v_mfma_f32_16x16x32_bf16 v[14:17], v[122:125], v[196:199], v[14:17]
	v_mfma_f32_16x16x32_bf16 v[82:85], v[94:97], v[212:215], v[50:53]
	v_mfma_f32_16x16x32_bf16 v[6:9], v[122:125], v[212:215], v[6:9]
	v_mfma_f32_16x16x32_bf16 v[50:53], v[126:129], v[176:179], v[54:57]
	v_mfma_f32_16x16x32_bf16 v[102:105], v[130:133], v[180:183], v[50:53]
	v_mfma_f32_16x16x32_bf16 v[50:53], v[126:129], v[184:187], v[58:61]
	v_mfma_f32_16x16x32_bf16 v[94:97], v[130:133], v[188:191], v[50:53]
	v_mfma_f32_16x16x32_bf16 v[50:53], v[126:129], v[192:195], v[86:89]
	v_mfma_f32_16x16x32_bf16 v[26:29], v[168:171], v[176:179], v[26:29]
	v_mfma_f32_16x16x32_bf16 v[18:21], v[168:171], v[184:187], v[18:21]
	v_mfma_f32_16x16x32_bf16 v[86:89], v[130:133], v[196:199], v[50:53]
	v_mfma_f32_16x16x32_bf16 v[10:13], v[168:171], v[192:195], v[10:13]
	v_mfma_f32_16x16x32_bf16 v[50:53], v[126:129], v[208:211], v[78:81]
	v_mfma_f32_16x16x32_bf16 v[2:5], v[168:171], v[208:211], v[2:5]
	v_mfma_f32_16x16x32_bf16 v[26:29], v[172:175], v[180:183], v[26:29]
	v_mfma_f32_16x16x32_bf16 v[18:21], v[172:175], v[188:191], v[18:21]
	v_mfma_f32_16x16x32_bf16 v[10:13], v[172:175], v[196:199], v[10:13]
	v_mfma_f32_16x16x32_bf16 v[78:81], v[130:133], v[212:215], v[50:53]
	v_mfma_f32_16x16x32_bf16 v[2:5], v[172:175], v[212:215], v[2:5]
	s_barrier
	s_movk_i32 s34, 0x100
	s_andn2_b64 vcc, exec, s[28:29]
	s_mov_b64 s[30:31], -1
	s_mov_b64 s[28:29], 0
	s_cbranch_vccz .LBB0_1860
	s_and_b64 vcc, exec, s[16:17]
	s_cbranch_vccz .LBB0_1863
	s_barrier

; #define PG8_STAGE(bufoff, gbase, voff) do { _Pragma("unroll") for (int _i = 0; _i < 2; ++_i) \
;         __builtin_amdgcn_global_load_lds((const unsigned*)((const char*)(gbase) + (voff)[_i]), (LAS unsigned*)(lds + (bufoff) + ldsw + _i * 8192), 16, 0, 0); } while (0)
; #define PG8_LDA(dst, b, h) do { _Pragma("unroll") for (int m = 0; m < 4; ++m) _Pragma("unroll") for (int k = 0; k < 2; ++k) dst[m][k] = *(const LAS bf16x8*)(lds + PG8_SA(b, h) + aoff + m * 2048 + k * 1024); } while (0)
; #define PG8_LDB(dst, b, h) do { _Pragma("unroll") for (int n = 0; n < 2; ++n) _Pragma("unroll") for (int k = 0; k < 2; ++k) dst[n][k] = *(const LAS bf16x8*)(lds + PG8_SB(b, h) + boff + n * 2048 + k * 1024); } while (0)
; #define PG8_WAIT_V(n) asm volatile("s_waitcnt vmcnt(" #n ")" ::: "memory")
; #define PG8_WAIT_L(n) asm volatile("s_waitcnt lgkmcnt(" #n ")" ::: "memory")
; #define PG8_BAR __builtin_amdgcn_s_barrier()
; #define PG8_SCHED __builtin_amdgcn_sched_barrier(0)
; template <class Epi, class Geom, class Sched, bool ALIGN_EPI, bool I8 = false>
; __device__ __forceinline__ void gemm_phase(LAS unsigned char* lds, const Gemm g, const Sched& S, const Epi& E) {
;     ...
;             PG8_LDB(B0, 0, 0); PG8_LDB(B1, 0, 1); PG8_SCHED; PG8_LDA(At, 0, 0); PG8_STAGE(PG8_SA(1, 1), a1 + hsA, voffA);
;             PG8_WAIT_V(8); PG8_WAIT_L(0); PG8_BAR; PG8_MMA(0, 0, At, B0); PG8_MMA(0, 1, At, B1); PG8_BAR; PG8_SCHED;
;             PG8_LDA(At, 0, 1); PG8_STAGE(PG8_SB(0, 0), b2, voffB); PG8_STAGE(PG8_SB(0, 1), b2 + hsB, voffB); PG8_STAGE(PG8_SA(0, 0), a2, voffA);
;             PG8_WAIT_V(8); PG8_WAIT_L(0); PG8_BAR; PG8_MMA(1, 0, At, B0); PG8_MMA(1, 1, At, B1); PG8_BAR; PG8_SCHED;
.LBB0_2231:
	ds_read_b128 v[102:105], v166
	ds_read_b128 v[106:109], v166 offset:1024
	ds_read_b128 v[114:117], v166 offset:2048
	ds_read_b128 v[118:121], v166 offset:3072
	ds_read_b128 v[156:159], v167
	ds_read_b128 v[170:173], v167 offset:1024
	ds_read_b128 v[174:177], v167 offset:2048
	ds_read_b128 v[178:181], v167 offset:3072
	s_add_u32 s34, s30, 0xfff80080
	s_addc_u32 s35, s31, -1
	s_cmp_eq_u32 s61, 28
	s_cselect_b32 s37, s23, s35
	s_cselect_b32 s36, s57, s34
	s_cselect_b32 s35, s21, s60
	s_cselect_b32 s34, s58, s59
	v_lshl_add_u64 v[160:161], s[30:31], 0, v[150:151]
	s_add_i32 m0, s29, 0xc000
	ds_read_b128 v[182:185], v168
	ds_read_b128 v[186:189], v168 offset:1024
	ds_read_b128 v[190:193], v168 offset:2048
	ds_read_b128 v[194:197], v168 offset:3072
	ds_read_b128 v[198:201], v168 offset:4096
	ds_read_b128 v[202:205], v168 offset:5120
	ds_read_b128 v[206:209], v168 offset:6144
	ds_read_b128 v[210:213], v168 offset:7168
	global_load_lds_dwordx4 v[160:161], off
	v_lshl_add_u64 v[160:161], s[30:31], 0, v[152:153]
	s_add_i32 m0, s29, 0xe000
	s_nop 0
	global_load_lds_dwordx4 v[160:161], off
	s_waitcnt vmcnt(8)
	s_waitcnt lgkmcnt(0)
	s_barrier
	v_mfma_i32_16x16x64_i8 v[142:145], v[102:105], v[182:185], v[142:145]
	v_mfma_i32_16x16x64_i8 v[138:141], v[114:117], v[182:185], v[138:141]
	v_mfma_i32_16x16x64_i8 v[126:129], v[102:105], v[190:193], v[126:129]
	v_mfma_i32_16x16x64_i8 v[122:125], v[114:117], v[190:193], v[122:125]
	v_mfma_i32_16x16x64_i8 v[94:97], v[102:105], v[198:201], v[94:97]
	v_mfma_i32_16x16x64_i8 v[90:93], v[114:117], v[198:201], v[90:93]
	v_mfma_i32_16x16x64_i8 v[82:85], v[102:105], v[206:209], v[82:85]
	v_mfma_i32_16x16x64_i8 v[74:77], v[114:117], v[206:209], v[74:77]
	v_mfma_i32_16x16x64_i8 v[142:145], v[106:109], v[186:189], v[142:145]
	v_mfma_i32_16x16x64_i8 v[138:141], v[118:121], v[186:189], v[138:141]
	v_mfma_i32_16x16x64_i8 v[126:129], v[106:109], v[194:197], v[126:129]
	v_mfma_i32_16x16x64_i8 v[122:125], v[118:121], v[194:197], v[122:125]
	v_mfma_i32_16x16x64_i8 v[94:97], v[106:109], v[202:205], v[94:97]
	v_mfma_i32_16x16x64_i8 v[90:93], v[118:121], v[202:205], v[90:93]
	v_mfma_i32_16x16x64_i8 v[82:85], v[106:109], v[210:213], v[82:85]
	v_mfma_i32_16x16x64_i8 v[74:77], v[118:121], v[210:213], v[74:77]
	v_mfma_i32_16x16x64_i8 v[134:137], v[156:159], v[182:185], v[134:137]
	v_mfma_i32_16x16x64_i8 v[130:133], v[174:177], v[182:185], v[130:133]
	v_mfma_i32_16x16x64_i8 v[110:113], v[156:159], v[190:193], v[110:113]
	v_mfma_i32_16x16x64_i8 v[98:101], v[174:177], v[190:193], v[98:101]
	v_mfma_i32_16x16x64_i8 v[86:89], v[156:159], v[198:201], v[86:89]
	v_mfma_i32_16x16x64_i8 v[78:81], v[174:177], v[198:201], v[78:81]
	v_mfma_i32_16x16x64_i8 v[70:73], v[156:159], v[206:209], v[70:73]
	v_mfma_i32_16x16x64_i8 v[66:69], v[174:177], v[206:209], v[66:69]
	v_mfma_i32_16x16x64_i8 v[134:137], v[170:173], v[186:189], v[134:137]
	v_mfma_i32_16x16x64_i8 v[130:133], v[178:181], v[186:189], v[130:133]
	v_mfma_i32_16x16x64_i8 v[110:113], v[170:173], v[194:197], v[110:113]
	v_mfma_i32_16x16x64_i8 v[98:101], v[178:181], v[194:197], v[98:101]
	v_mfma_i32_16x16x64_i8 v[86:89], v[170:173], v[202:205], v[86:89]
	v_mfma_i32_16x16x64_i8 v[78:81], v[178:181], v[202:205], v[78:81]
	v_mfma_i32_16x16x64_i8 v[70:73], v[170:173], v[210:213], v[70:73]
	v_mfma_i32_16x16x64_i8 v[66:69], v[178:181], v[210:213], v[66:69]
	s_barrier
	s_add_i32 s62, s10, s41
	v_lshl_add_u64 v[160:161], s[34:35], 0, v[146:147]
	s_mov_b32 m0, s62
	ds_read_b128 v[182:185], v168 offset:16384
	ds_read_b128 v[186:189], v168 offset:17408
	ds_read_b128 v[190:193], v168 offset:18432
	ds_read_b128 v[194:197], v168 offset:19456
	ds_read_b128 v[198:201], v168 offset:20480
	ds_read_b128 v[202:205], v168 offset:21504
	ds_read_b128 v[206:209], v168 offset:22528
	ds_read_b128 v[210:213], v168 offset:23552
	global_load_lds_dwordx4 v[160:161], off
	s_add_i32 m0, s62, 0x2000
	s_add_u32 s62, s34, 0x80000
	v_lshl_add_u64 v[214:215], s[34:35], 0, v[148:149]
	s_addc_u32 s63, s35, 0
	s_add_i32 s64, s50, s41
	global_load_lds_dwordx4 v[214:215], off
	v_lshl_add_u64 v[216:217], s[62:63], 0, v[146:147]
	s_mov_b32 m0, s64
	v_lshl_add_u64 v[218:219], s[36:37], 0, v[148:149]
	global_load_lds_dwordx4 v[216:217], off
	v_lshl_add_u64 v[216:217], s[62:63], 0, v[148:149]
	s_add_i32 m0, s64, 0x2000
	s_nop 0
	global_load_lds_dwordx4 v[216:217], off
	v_lshl_add_u64 v[216:217], s[36:37], 0, v[146:147]
	s_mov_b32 m0, s29
	s_nop 0
	global_load_lds_dwordx4 v[216:217], off
	s_mov_b32 m0, s44
	s_nop 0
	global_load_lds_dwordx4 v[218:219], off
	s_waitcnt vmcnt(8)
	s_waitcnt lgkmcnt(0)
	s_barrier
; #define PG8_STAGE(bufoff, gbase, voff) do { _Pragma("unroll") for (int _i = 0; _i < 2; ++_i) \
;         __builtin_amdgcn_global_load_lds((const unsigned*)((const char*)(gbase) + (voff)[_i]), (LAS unsigned*)(lds + (bufoff) + ldsw + _i * 8192), 16, 0, 0); } while (0)
; #define PG8_LDA(dst, b, h) do { _Pragma("unroll") for (int m = 0; m < 4; ++m) _Pragma("unroll") for (int k = 0; k < 2; ++k) dst[m][k] = *(const LAS bf16x8*)(lds + PG8_SA(b, h) + aoff + m * 2048 + k * 1024); } while (0)
; #define PG8_LDB(dst, b, h) do { _Pragma("unroll") for (int n = 0; n < 2; ++n) _Pragma("unroll") for (int k = 0; k < 2; ++k) dst[n][k] = *(const LAS bf16x8*)(lds + PG8_SB(b, h) + boff + n * 2048 + k * 1024); } while (0)
; #define PG8_WAIT_V(n) asm volatile("s_waitcnt vmcnt(" #n ")" ::: "memory")
; #define PG8_WAIT_L(n) asm volatile("s_waitcnt lgkmcnt(" #n ")" ::: "memory")
; #define PG8_BAR __builtin_amdgcn_s_barrier()
; #define PG8_SCHED __builtin_amdgcn_sched_barrier(0)
; template <class Epi, class Geom, class Sched, bool ALIGN_EPI, bool I8 = false>
; __device__ __forceinline__ void gemm_phase(LAS unsigned char* lds, const Gemm g, const Sched& S, const Epi& E) {
;     ...
;             PG8_WAIT_V(8); PG8_WAIT_L(0); PG8_BAR; PG8_MMA(1, 0, At, B0); PG8_MMA(1, 1, At, B1); PG8_BAR; PG8_SCHED;
;             PG8_LDB(B0, 1, 0); PG8_LDB(B1, 1, 1); PG8_SCHED; PG8_LDA(At, 1, 0); PG8_STAGE(PG8_SA(0, 1), a2 + hsA, voffA);
;             PG8_WAIT_V(8); PG8_WAIT_L(0); PG8_BAR; PG8_MMA(0, 0, At, B0); PG8_MMA(0, 1, At, B1); PG8_BAR; PG8_SCHED;
	v_mfma_i32_16x16x64_i8 v[62:65], v[102:105], v[182:185], v[62:65]
	v_mfma_i32_16x16x64_i8 v[58:61], v[114:117], v[182:185], v[58:61]
	v_mfma_i32_16x16x64_i8 v[50:53], v[102:105], v[190:193], v[50:53]
	v_mfma_i32_16x16x64_i8 v[42:45], v[114:117], v[190:193], v[42:45]
	v_mfma_i32_16x16x64_i8 v[30:33], v[102:105], v[198:201], v[30:33]
	v_mfma_i32_16x16x64_i8 v[26:29], v[114:117], v[198:201], v[26:29]
	v_mfma_i32_16x16x64_i8 v[18:21], v[102:105], v[206:209], v[18:21]
	v_mfma_i32_16x16x64_i8 v[10:13], v[114:117], v[206:209], v[10:13]
	v_mfma_i32_16x16x64_i8 v[62:65], v[106:109], v[186:189], v[62:65]
	v_mfma_i32_16x16x64_i8 v[58:61], v[118:121], v[186:189], v[58:61]
	v_mfma_i32_16x16x64_i8 v[50:53], v[106:109], v[194:197], v[50:53]
	v_mfma_i32_16x16x64_i8 v[42:45], v[118:121], v[194:197], v[42:45]
	v_mfma_i32_16x16x64_i8 v[30:33], v[106:109], v[202:205], v[30:33]
	v_mfma_i32_16x16x64_i8 v[26:29], v[118:121], v[202:205], v[26:29]
	v_mfma_i32_16x16x64_i8 v[18:21], v[106:109], v[210:213], v[18:21]
	v_mfma_i32_16x16x64_i8 v[10:13], v[118:121], v[210:213], v[10:13]
	v_mfma_i32_16x16x64_i8 v[54:57], v[156:159], v[182:185], v[54:57]
	v_mfma_i32_16x16x64_i8 v[46:49], v[174:177], v[182:185], v[46:49]
	v_mfma_i32_16x16x64_i8 v[38:41], v[156:159], v[190:193], v[38:41]
	v_mfma_i32_16x16x64_i8 v[34:37], v[174:177], v[190:193], v[34:37]
	v_mfma_i32_16x16x64_i8 v[22:25], v[156:159], v[198:201], v[22:25]
	v_mfma_i32_16x16x64_i8 v[14:17], v[174:177], v[198:201], v[14:17]
	v_mfma_i32_16x16x64_i8 v[6:9], v[156:159], v[206:209], v[6:9]
	v_mfma_i32_16x16x64_i8 v[2:5], v[174:177], v[206:209], v[2:5]
	v_mfma_i32_16x16x64_i8 v[54:57], v[170:173], v[186:189], v[54:57]
	v_mfma_i32_16x16x64_i8 v[46:49], v[178:181], v[186:189], v[46:49]
	v_mfma_i32_16x16x64_i8 v[38:41], v[170:173], v[194:197], v[38:41]
	v_mfma_i32_16x16x64_i8 v[34:37], v[178:181], v[194:197], v[34:37]
	v_mfma_i32_16x16x64_i8 v[22:25], v[170:173], v[202:205], v[22:25]
	v_mfma_i32_16x16x64_i8 v[14:17], v[178:181], v[202:205], v[14:17]
	v_mfma_i32_16x16x64_i8 v[6:9], v[170:173], v[210:213], v[6:9]
	v_mfma_i32_16x16x64_i8 v[2:5], v[178:181], v[210:213], v[2:5]
	s_barrier
	s_add_i32 s62, 0, 0x18000
	s_add_i32 s63, 0, 0x1c000
	v_add_u32_e32 v118, s62, v164
	v_add_u32_e32 v162, s63, v164
	ds_read_b128 v[102:105], v118
	ds_read_b128 v[106:109], v118 offset:1024
	ds_read_b128 v[114:117], v118 offset:2048
	ds_read_b128 v[118:121], v118 offset:3072
	ds_read_b128 v[156:159], v162
	ds_read_b128 v[170:173], v162 offset:1024
	ds_read_b128 v[174:177], v162 offset:2048
	ds_read_b128 v[178:181], v162 offset:3072
	s_add_u32 s36, s36, 0x80000
	s_addc_u32 s37, s37, 0
	s_mov_b32 m0, s45
	v_lshl_add_u64 v[220:221], s[36:37], 0, v[146:147]
	ds_read_b128 v[182:185], v168 offset:32768
	ds_read_b128 v[186:189], v168 offset:33792
	ds_read_b128 v[190:193], v168 offset:34816
	ds_read_b128 v[194:197], v168 offset:35840
	ds_read_b128 v[198:201], v168 offset:36864
	ds_read_b128 v[202:205], v168 offset:37888
	ds_read_b128 v[206:209], v168 offset:38912
	ds_read_b128 v[210:213], v168 offset:39936
	global_load_lds_dwordx4 v[220:221], off
	v_lshl_add_u64 v[220:221], s[36:37], 0, v[148:149]
	s_mov_b32 m0, s46
	s_nop 0
	global_load_lds_dwordx4 v[220:221], off
	s_waitcnt vmcnt(8)
	s_waitcnt lgkmcnt(0)
	s_barrier
	v_mfma_i32_16x16x64_i8 v[142:145], v[102:105], v[182:185], v[142:145]
	v_mfma_i32_16x16x64_i8 v[138:141], v[114:117], v[182:185], v[138:141]
	v_mfma_i32_16x16x64_i8 v[126:129], v[102:105], v[190:193], v[126:129]
	v_mfma_i32_16x16x64_i8 v[122:125], v[114:117], v[190:193], v[122:125]
	v_mfma_i32_16x16x64_i8 v[94:97], v[102:105], v[198:201], v[94:97]
	v_mfma_i32_16x16x64_i8 v[90:93], v[114:117], v[198:201], v[90:93]
	v_mfma_i32_16x16x64_i8 v[82:85], v[102:105], v[206:209], v[82:85]
	v_mfma_i32_16x16x64_i8 v[74:77], v[114:117], v[206:209], v[74:77]
	v_mfma_i32_16x16x64_i8 v[142:145], v[106:109], v[186:189], v[142:145]
	v_mfma_i32_16x16x64_i8 v[138:141], v[118:121], v[186:189], v[138:141]
	v_mfma_i32_16x16x64_i8 v[126:129], v[106:109], v[194:197], v[126:129]
	v_mfma_i32_16x16x64_i8 v[122:125], v[118:121], v[194:197], v[122:125]
	v_mfma_i32_16x16x64_i8 v[94:97], v[106:109], v[202:205], v[94:97]
	v_mfma_i32_16x16x64_i8 v[90:93], v[118:121], v[202:205], v[90:93]
	v_mfma_i32_16x16x64_i8 v[82:85], v[106:109], v[210:213], v[82:85]
	v_mfma_i32_16x16x64_i8 v[74:77], v[118:121], v[210:213], v[74:77]
	v_mfma_i32_16x16x64_i8 v[134:137], v[156:159], v[182:185], v[134:137]
	v_mfma_i32_16x16x64_i8 v[130:133], v[174:177], v[182:185], v[130:133]
	v_mfma_i32_16x16x64_i8 v[110:113], v[156:159], v[190:193], v[110:113]
	v_mfma_i32_16x16x64_i8 v[98:101], v[174:177], v[190:193], v[98:101]
	v_mfma_i32_16x16x64_i8 v[86:89], v[156:159], v[198:201], v[86:89]
	v_mfma_i32_16x16x64_i8 v[78:81], v[174:177], v[198:201], v[78:81]
	v_mfma_i32_16x16x64_i8 v[70:73], v[156:159], v[206:209], v[70:73]
	v_mfma_i32_16x16x64_i8 v[66:69], v[174:177], v[206:209], v[66:69]
	v_mfma_i32_16x16x64_i8 v[134:137], v[170:173], v[186:189], v[134:137]
	v_mfma_i32_16x16x64_i8 v[130:133], v[178:181], v[186:189], v[130:133]
	v_mfma_i32_16x16x64_i8 v[110:113], v[170:173], v[194:197], v[110:113]
	v_mfma_i32_16x16x64_i8 v[98:101], v[178:181], v[194:197], v[98:101]
	v_mfma_i32_16x16x64_i8 v[86:89], v[170:173], v[202:205], v[86:89]
	v_mfma_i32_16x16x64_i8 v[78:81], v[178:181], v[202:205], v[78:81]
	v_mfma_i32_16x16x64_i8 v[70:73], v[170:173], v[210:213], v[70:73]
	v_mfma_i32_16x16x64_i8 v[66:69], v[178:181], v[210:213], v[66:69]
	s_barrier
; #define PG8_STAGE(bufoff, gbase, voff) do { _Pragma("unroll") for (int _i = 0; _i < 2; ++_i) \
;         __builtin_amdgcn_global_load_lds((const unsigned*)((const char*)(gbase) + (voff)[_i]), (LAS unsigned*)(lds + (bufoff) + ldsw + _i * 8192), 16, 0, 0); } while (0)
; #define PG8_LDA(dst, b, h) do { _Pragma("unroll") for (int m = 0; m < 4; ++m) _Pragma("unroll") for (int k = 0; k < 2; ++k) dst[m][k] = *(const LAS bf16x8*)(lds + PG8_SA(b, h) + aoff + m * 2048 + k * 1024); } while (0)
; #define PG8_WAIT_V(n) asm volatile("s_waitcnt vmcnt(" #n ")" ::: "memory")
; #define PG8_WAIT_L(n) asm volatile("s_waitcnt lgkmcnt(" #n ")" ::: "memory")
; #define PG8_BAR __builtin_amdgcn_s_barrier()
; #define PG8_SCHED __builtin_amdgcn_sched_barrier(0)
; template <class Epi, class Geom, class Sched, bool ALIGN_EPI, bool I8 = false>
; __device__ __forceinline__ void gemm_phase(LAS unsigned char* lds, const Gemm g, const Sched& S, const Epi& E) {
;     ...
;             PG8_LDA(At, 1, 1); PG8_STAGE(PG8_SB(1, 0), b3, voffB); PG8_STAGE(PG8_SB(1, 1), b3 + hsB, voffB); PG8_STAGE(PG8_SA(1, 0), a3, voffA);
;             PG8_WAIT_V(8); PG8_WAIT_L(0); PG8_BAR; PG8_MMA(1, 0, At, B0); PG8_MMA(1, 1, At, B1); PG8_BAR; PG8_SCHED;
;         }
	s_add_i32 s36, s62, s41
	v_lshl_add_u64 v[160:161], v[160:161], 0, s[16:17]
	s_mov_b32 m0, s36
	ds_read_b128 v[182:185], v168 offset:49152
	ds_read_b128 v[186:189], v168 offset:50176
	ds_read_b128 v[190:193], v168 offset:51200
	ds_read_b128 v[194:197], v168 offset:52224
	ds_read_b128 v[198:201], v168 offset:53248
	ds_read_b128 v[202:205], v168 offset:54272
	ds_read_b128 v[206:209], v168 offset:55296
	ds_read_b128 v[210:213], v168 offset:56320
	global_load_lds_dwordx4 v[160:161], off
	s_add_i32 m0, s36, 0x2000
	s_add_u32 s34, s34, 0x80080
	v_lshl_add_u64 v[160:161], v[214:215], 0, s[16:17]
	s_addc_u32 s35, s35, 0
	s_add_i32 s36, s63, s41
	global_load_lds_dwordx4 v[160:161], off
	v_lshl_add_u64 v[160:161], s[34:35], 0, v[146:147]
	s_mov_b32 m0, s36
	s_nop 0
	global_load_lds_dwordx4 v[160:161], off
	v_lshl_add_u64 v[160:161], s[34:35], 0, v[148:149]
	s_add_i32 m0, s36, 0x2000
	s_nop 0
	global_load_lds_dwordx4 v[160:161], off
	v_lshl_add_u64 v[160:161], v[216:217], 0, s[16:17]
	s_mov_b32 m0, s47
	s_nop 0
	global_load_lds_dwordx4 v[160:161], off
	v_lshl_add_u64 v[160:161], v[218:219], 0, s[16:17]
	s_mov_b32 m0, s48
	s_nop 0
	global_load_lds_dwordx4 v[160:161], off
	s_waitcnt vmcnt(8)
	s_waitcnt lgkmcnt(0)
	s_barrier
	v_mfma_i32_16x16x64_i8 v[62:65], v[102:105], v[182:185], v[62:65]
	v_mfma_i32_16x16x64_i8 v[58:61], v[114:117], v[182:185], v[58:61]
	v_mfma_i32_16x16x64_i8 v[50:53], v[102:105], v[190:193], v[50:53]
	v_mfma_i32_16x16x64_i8 v[42:45], v[114:117], v[190:193], v[42:45]
	v_mfma_i32_16x16x64_i8 v[30:33], v[102:105], v[198:201], v[30:33]
	v_mfma_i32_16x16x64_i8 v[26:29], v[114:117], v[198:201], v[26:29]
	v_mfma_i32_16x16x64_i8 v[18:21], v[102:105], v[206:209], v[18:21]
	v_mfma_i32_16x16x64_i8 v[10:13], v[114:117], v[206:209], v[10:13]
	v_mfma_i32_16x16x64_i8 v[62:65], v[106:109], v[186:189], v[62:65]
	v_mfma_i32_16x16x64_i8 v[58:61], v[118:121], v[186:189], v[58:61]
	v_mfma_i32_16x16x64_i8 v[50:53], v[106:109], v[194:197], v[50:53]
	v_mfma_i32_16x16x64_i8 v[42:45], v[118:121], v[194:197], v[42:45]
	v_mfma_i32_16x16x64_i8 v[30:33], v[106:109], v[202:205], v[30:33]
	v_mfma_i32_16x16x64_i8 v[26:29], v[118:121], v[202:205], v[26:29]
	v_mfma_i32_16x16x64_i8 v[18:21], v[106:109], v[210:213], v[18:21]
	v_mfma_i32_16x16x64_i8 v[10:13], v[118:121], v[210:213], v[10:13]
	v_mfma_i32_16x16x64_i8 v[54:57], v[156:159], v[182:185], v[54:57]
	v_mfma_i32_16x16x64_i8 v[46:49], v[174:177], v[182:185], v[46:49]
	v_mfma_i32_16x16x64_i8 v[38:41], v[156:159], v[190:193], v[38:41]
	v_mfma_i32_16x16x64_i8 v[34:37], v[174:177], v[190:193], v[34:37]
	v_mfma_i32_16x16x64_i8 v[22:25], v[156:159], v[198:201], v[22:25]
	v_mfma_i32_16x16x64_i8 v[14:17], v[174:177], v[198:201], v[14:17]
	v_mfma_i32_16x16x64_i8 v[6:9], v[156:159], v[206:209], v[6:9]
	v_mfma_i32_16x16x64_i8 v[2:5], v[174:177], v[206:209], v[2:5]
	v_mfma_i32_16x16x64_i8 v[54:57], v[170:173], v[186:189], v[54:57]
	v_mfma_i32_16x16x64_i8 v[46:49], v[178:181], v[186:189], v[46:49]
	v_mfma_i32_16x16x64_i8 v[38:41], v[170:173], v[194:197], v[38:41]
	v_mfma_i32_16x16x64_i8 v[34:37], v[178:181], v[194:197], v[34:37]
	v_mfma_i32_16x16x64_i8 v[22:25], v[170:173], v[202:205], v[22:25]
	v_mfma_i32_16x16x64_i8 v[14:17], v[178:181], v[202:205], v[14:17]
	v_mfma_i32_16x16x64_i8 v[6:9], v[170:173], v[210:213], v[6:9]
	v_mfma_i32_16x16x64_i8 v[2:5], v[178:181], v[210:213], v[2:5]
	s_barrier
	s_add_i32 s61, s61, 2
	s_add_u32 s30, s30, 0x100
	s_addc_u32 s31, s31, 0
	s_add_u32 s59, s59, 0x100
	s_addc_u32 s60, s60, 0
	s_cmp_gt_u32 s61, 29
	s_cbranch_scc0 .LBB0_2231
	s_and_b64 vcc, exec, s[18:19]
	s_cbranch_vccz .LBB0_2234
	s_barrier

; #define PG8_STAGE(bufoff, gbase, voff) do { _Pragma("unroll") for (int _i = 0; _i < 2; ++_i) \
;         __builtin_amdgcn_global_load_lds((const unsigned*)((const char*)(gbase) + (voff)[_i]), (LAS unsigned*)(lds + (bufoff) + ldsw + _i * 8192), 16, 0, 0); } while (0)
; #define PG8_LDA(dst, b, h) do { _Pragma("unroll") for (int m = 0; m < 4; ++m) _Pragma("unroll") for (int k = 0; k < 2; ++k) dst[m][k] = *(const LAS bf16x8*)(lds + PG8_SA(b, h) + aoff + m * 2048 + k * 1024); } while (0)
; #define PG8_LDB(dst, b, h) do { _Pragma("unroll") for (int n = 0; n < 2; ++n) _Pragma("unroll") for (int k = 0; k < 2; ++k) dst[n][k] = *(const LAS bf16x8*)(lds + PG8_SB(b, h) + boff + n * 2048 + k * 1024); } while (0)
; #define PG8_WAIT_V(n) asm volatile("s_waitcnt vmcnt(" #n ")" ::: "memory")
; #define PG8_WAIT_L(n) asm volatile("s_waitcnt lgkmcnt(" #n ")" ::: "memory")
; #define PG8_BAR __builtin_amdgcn_s_barrier()
; #define PG8_SCHED __builtin_amdgcn_sched_barrier(0)
; template <class Epi, class Geom, class Sched, bool ALIGN_EPI, bool I8 = false>
; __device__ __forceinline__ void gemm_phase(LAS unsigned char* lds, const Gemm g, const Sched& S, const Epi& E) {
;     ...
;             PG8_LDB(B0, 0, 0); PG8_LDB(B1, 0, 1); PG8_SCHED; PG8_LDA(At, 0, 0); PG8_STAGE(PG8_SA(1, 1), a1 + hsA, voffA);
;             PG8_WAIT_V(8); PG8_WAIT_L(0); PG8_BAR; PG8_MMA(0, 0, At, B0); PG8_MMA(0, 1, At, B1); PG8_BAR; PG8_SCHED;
;             PG8_LDA(At, 0, 1); PG8_STAGE(PG8_SB(0, 0), b2, voffB); PG8_STAGE(PG8_SB(0, 1), b2 + hsB, voffB); PG8_STAGE(PG8_SA(0, 0), a2, voffA);
;             PG8_WAIT_V(8); PG8_WAIT_L(0); PG8_BAR; PG8_MMA(1, 0, At, B0); PG8_MMA(1, 1, At, B1); PG8_BAR; PG8_SCHED;
.LBB0_2243:
	s_add_i32 s20, s24, 0x100
	s_and_b64 s[18:19], s[18:19], exec
	s_cselect_b32 s19, 0, s20
	s_cselect_b32 s18, 0, 0
	s_add_u32 s20, s10, s19
	s_addc_u32 s21, s11, s18
	s_add_u32 s22, s4, s19
	v_add_u32_e32 v127, s41, v1
	s_addc_u32 s23, s5, s18
	ds_read_b128 v[128:131], v127
	ds_read_b128 v[132:135], v127 offset:1024
	ds_read_b128 v[136:139], v127 offset:2048
	ds_read_b128 v[152:155], v127 offset:3072
	v_add_u32_e32 v127, s42, v1
	s_add_u32 s28, s12, s24
	ds_read_b128 v[156:159], v127
	ds_read_b128 v[160:163], v127 offset:1024
	ds_read_b128 v[164:167], v127 offset:2048
	ds_read_b128 v[168:171], v127 offset:3072
	s_addc_u32 s29, s13, 0
	s_add_u32 s24, s22, 0x80000
	s_addc_u32 s25, s23, 0
	s_add_u32 s18, s20, 0x80000
	s_addc_u32 s19, s21, 0
	s_add_u32 s26, s22, 0x80080
	s_addc_u32 s27, s23, 0
	v_lshl_add_u64 v[140:141], s[28:29], 0, v[146:147]
	s_mov_b32 m0, s43
	v_lshl_add_u64 v[140:141], v[140:141], 0, s[14:15]
	ds_read_b128 v[172:175], v126
	ds_read_b128 v[176:179], v126 offset:1024
	ds_read_b128 v[180:183], v126 offset:2048
	ds_read_b128 v[184:187], v126 offset:3072
	ds_read_b128 v[188:191], v126 offset:4096
	ds_read_b128 v[192:195], v126 offset:5120
	ds_read_b128 v[196:199], v126 offset:6144
	ds_read_b128 v[200:203], v126 offset:7168
	global_load_lds_dwordx4 v[140:141], off
	v_lshl_add_u64 v[140:141], s[28:29], 0, v[148:149]
	v_lshl_add_u64 v[140:141], v[140:141], 0, s[14:15]
	s_mov_b32 m0, s44
	s_nop 0
	global_load_lds_dwordx4 v[140:141], off
	s_waitcnt vmcnt(8)
	s_waitcnt lgkmcnt(0)
	s_barrier
	v_mfma_i32_16x16x64_i8 v[140:143], v[128:131], v[172:175], v[142:145]
	v_mfma_i32_16x16x64_i8 v[122:125], v[136:139], v[172:175], v[122:125]
	v_mfma_i32_16x16x64_i8 v[110:113], v[128:131], v[180:183], v[110:113]
	v_mfma_i32_16x16x64_i8 v[106:109], v[136:139], v[180:183], v[106:109]
	v_mfma_i32_16x16x64_i8 v[94:97], v[128:131], v[188:191], v[94:97]
	v_mfma_i32_16x16x64_i8 v[90:93], v[136:139], v[188:191], v[90:93]
	v_mfma_i32_16x16x64_i8 v[78:81], v[128:131], v[196:199], v[78:81]
	v_mfma_i32_16x16x64_i8 v[74:77], v[136:139], v[196:199], v[74:77]
	v_mfma_i32_16x16x64_i8 v[140:143], v[132:135], v[176:179], v[140:143]
	v_mfma_i32_16x16x64_i8 v[122:125], v[152:155], v[176:179], v[122:125]
	v_mfma_i32_16x16x64_i8 v[110:113], v[132:135], v[184:187], v[110:113]
	v_mfma_i32_16x16x64_i8 v[106:109], v[152:155], v[184:187], v[106:109]
	v_mfma_i32_16x16x64_i8 v[94:97], v[132:135], v[192:195], v[94:97]
	v_mfma_i32_16x16x64_i8 v[90:93], v[152:155], v[192:195], v[90:93]
	v_mfma_i32_16x16x64_i8 v[78:81], v[132:135], v[200:203], v[78:81]
	v_mfma_i32_16x16x64_i8 v[74:77], v[152:155], v[200:203], v[74:77]
	v_mfma_i32_16x16x64_i8 v[118:121], v[156:159], v[172:175], v[118:121]
	v_mfma_i32_16x16x64_i8 v[114:117], v[164:167], v[172:175], v[114:117]
	v_mfma_i32_16x16x64_i8 v[102:105], v[156:159], v[180:183], v[102:105]
	v_mfma_i32_16x16x64_i8 v[98:101], v[164:167], v[180:183], v[98:101]
	v_mfma_i32_16x16x64_i8 v[86:89], v[156:159], v[188:191], v[86:89]
	v_mfma_i32_16x16x64_i8 v[82:85], v[164:167], v[188:191], v[82:85]
	v_mfma_i32_16x16x64_i8 v[70:73], v[156:159], v[196:199], v[70:73]
	v_mfma_i32_16x16x64_i8 v[66:69], v[164:167], v[196:199], v[66:69]
	v_mfma_i32_16x16x64_i8 v[118:121], v[160:163], v[176:179], v[118:121]
	v_mfma_i32_16x16x64_i8 v[114:117], v[168:171], v[176:179], v[114:117]
	v_mfma_i32_16x16x64_i8 v[102:105], v[160:163], v[184:187], v[102:105]
	v_mfma_i32_16x16x64_i8 v[98:101], v[168:171], v[184:187], v[98:101]
	v_mfma_i32_16x16x64_i8 v[86:89], v[160:163], v[192:195], v[86:89]
	v_mfma_i32_16x16x64_i8 v[82:85], v[168:171], v[192:195], v[82:85]
	v_mfma_i32_16x16x64_i8 v[70:73], v[160:163], v[200:203], v[70:73]
	v_mfma_i32_16x16x64_i8 v[66:69], v[168:171], v[200:203], v[66:69]
	s_barrier
	s_mov_b32 m0, s45
	v_lshl_add_u64 v[204:205], s[22:23], 0, v[146:147]
	ds_read_b128 v[172:175], v126 offset:16384
	ds_read_b128 v[176:179], v126 offset:17408
	ds_read_b128 v[180:183], v126 offset:18432
	ds_read_b128 v[184:187], v126 offset:19456
	ds_read_b128 v[188:191], v126 offset:20480
	ds_read_b128 v[192:195], v126 offset:21504
	ds_read_b128 v[196:199], v126 offset:22528
	ds_read_b128 v[200:203], v126 offset:23552
	global_load_lds_dwordx4 v[204:205], off
	v_lshl_add_u64 v[206:207], s[22:23], 0, v[148:149]
	s_mov_b32 m0, s46
	v_lshl_add_u64 v[144:145], s[24:25], 0, v[146:147]
	global_load_lds_dwordx4 v[206:207], off
	s_mov_b32 m0, s47
	v_lshl_add_u64 v[208:209], s[20:21], 0, v[146:147]
	global_load_lds_dwordx4 v[144:145], off
	v_lshl_add_u64 v[144:145], s[24:25], 0, v[148:149]
	s_mov_b32 m0, s48
	v_lshl_add_u64 v[210:211], s[20:21], 0, v[148:149]
	global_load_lds_dwordx4 v[144:145], off
	s_mov_b32 m0, s36
	s_nop 0
	global_load_lds_dwordx4 v[208:209], off
	s_mov_b32 m0, s33
	s_nop 0
	global_load_lds_dwordx4 v[210:211], off
	s_waitcnt vmcnt(8)
	s_waitcnt lgkmcnt(0)
	s_barrier
; #define PG8_STAGE(bufoff, gbase, voff) do { _Pragma("unroll") for (int _i = 0; _i < 2; ++_i) \
;         __builtin_amdgcn_global_load_lds((const unsigned*)((const char*)(gbase) + (voff)[_i]), (LAS unsigned*)(lds + (bufoff) + ldsw + _i * 8192), 16, 0, 0); } while (0)
; #define PG8_LDA(dst, b, h) do { _Pragma("unroll") for (int m = 0; m < 4; ++m) _Pragma("unroll") for (int k = 0; k < 2; ++k) dst[m][k] = *(const LAS bf16x8*)(lds + PG8_SA(b, h) + aoff + m * 2048 + k * 1024); } while (0)
; #define PG8_LDB(dst, b, h) do { _Pragma("unroll") for (int n = 0; n < 2; ++n) _Pragma("unroll") for (int k = 0; k < 2; ++k) dst[n][k] = *(const LAS bf16x8*)(lds + PG8_SB(b, h) + boff + n * 2048 + k * 1024); } while (0)
; #define PG8_WAIT_V(n) asm volatile("s_waitcnt vmcnt(" #n ")" ::: "memory")
; #define PG8_WAIT_L(n) asm volatile("s_waitcnt lgkmcnt(" #n ")" ::: "memory")
; #define PG8_BAR __builtin_amdgcn_s_barrier()
; #define PG8_SCHED __builtin_amdgcn_sched_barrier(0)
; template <class Epi, class Geom, class Sched, bool ALIGN_EPI, bool I8 = false>
; __device__ __forceinline__ void gemm_phase(LAS unsigned char* lds, const Gemm g, const Sched& S, const Epi& E) {
;     ...
;             PG8_WAIT_V(8); PG8_WAIT_L(0); PG8_BAR; PG8_MMA(1, 0, At, B0); PG8_MMA(1, 1, At, B1); PG8_BAR; PG8_SCHED;
;             PG8_LDB(B0, 1, 0); PG8_LDB(B1, 1, 1); PG8_SCHED; PG8_LDA(At, 1, 0); PG8_STAGE(PG8_SA(0, 1), a2 + hsA, voffA);
;             PG8_WAIT_V(8); PG8_WAIT_L(0); PG8_BAR; PG8_MMA(0, 0, At, B0); PG8_MMA(0, 1, At, B1); PG8_BAR; PG8_SCHED;
	v_mfma_i32_16x16x64_i8 v[62:65], v[128:131], v[172:175], v[62:65]
	v_mfma_i32_16x16x64_i8 v[58:61], v[136:139], v[172:175], v[58:61]
	v_mfma_i32_16x16x64_i8 v[46:49], v[128:131], v[180:183], v[46:49]
	v_mfma_i32_16x16x64_i8 v[42:45], v[136:139], v[180:183], v[42:45]
	v_mfma_i32_16x16x64_i8 v[30:33], v[128:131], v[188:191], v[30:33]
	v_mfma_i32_16x16x64_i8 v[26:29], v[136:139], v[188:191], v[26:29]
	v_mfma_i32_16x16x64_i8 v[14:17], v[128:131], v[196:199], v[14:17]
	v_mfma_i32_16x16x64_i8 v[10:13], v[136:139], v[196:199], v[10:13]
	v_mfma_i32_16x16x64_i8 v[62:65], v[132:135], v[176:179], v[62:65]
	v_mfma_i32_16x16x64_i8 v[58:61], v[152:155], v[176:179], v[58:61]
	v_mfma_i32_16x16x64_i8 v[46:49], v[132:135], v[184:187], v[46:49]
	v_mfma_i32_16x16x64_i8 v[42:45], v[152:155], v[184:187], v[42:45]
	v_mfma_i32_16x16x64_i8 v[30:33], v[132:135], v[192:195], v[30:33]
	v_mfma_i32_16x16x64_i8 v[26:29], v[152:155], v[192:195], v[26:29]
	v_mfma_i32_16x16x64_i8 v[14:17], v[132:135], v[200:203], v[14:17]
	v_mfma_i32_16x16x64_i8 v[10:13], v[152:155], v[200:203], v[10:13]
	v_mfma_i32_16x16x64_i8 v[54:57], v[156:159], v[172:175], v[54:57]
	v_mfma_i32_16x16x64_i8 v[50:53], v[164:167], v[172:175], v[50:53]
	v_mfma_i32_16x16x64_i8 v[38:41], v[156:159], v[180:183], v[38:41]
	v_mfma_i32_16x16x64_i8 v[34:37], v[164:167], v[180:183], v[34:37]
	v_mfma_i32_16x16x64_i8 v[22:25], v[156:159], v[188:191], v[22:25]
	v_mfma_i32_16x16x64_i8 v[18:21], v[164:167], v[188:191], v[18:21]
	v_mfma_i32_16x16x64_i8 v[6:9], v[156:159], v[196:199], v[6:9]
	v_mfma_i32_16x16x64_i8 v[2:5], v[164:167], v[196:199], v[2:5]
	v_mfma_i32_16x16x64_i8 v[54:57], v[160:163], v[176:179], v[54:57]
	v_mfma_i32_16x16x64_i8 v[50:53], v[168:171], v[176:179], v[50:53]
	v_mfma_i32_16x16x64_i8 v[38:41], v[160:163], v[184:187], v[38:41]
	v_mfma_i32_16x16x64_i8 v[34:37], v[168:171], v[184:187], v[34:37]
	v_mfma_i32_16x16x64_i8 v[22:25], v[160:163], v[192:195], v[22:25]
	v_mfma_i32_16x16x64_i8 v[18:21], v[168:171], v[192:195], v[18:21]
	v_mfma_i32_16x16x64_i8 v[6:9], v[160:163], v[200:203], v[6:9]
	v_mfma_i32_16x16x64_i8 v[2:5], v[168:171], v[200:203], v[2:5]
	s_barrier
	v_add_u32_e32 v127, s49, v1
	ds_read_b128 v[128:131], v127
	ds_read_b128 v[132:135], v127 offset:1024
	ds_read_b128 v[136:139], v127 offset:2048
	ds_read_b128 v[152:155], v127 offset:3072
	v_add_u32_e32 v127, s50, v1
	ds_read_b128 v[156:159], v127
	ds_read_b128 v[160:163], v127 offset:1024
	ds_read_b128 v[164:167], v127 offset:2048
	ds_read_b128 v[168:171], v127 offset:3072
	s_mov_b32 m0, s37
	v_lshl_add_u64 v[144:145], s[18:19], 0, v[146:147]
	ds_read_b128 v[172:175], v126 offset:32768
	ds_read_b128 v[176:179], v126 offset:33792
	ds_read_b128 v[180:183], v126 offset:34816
	ds_read_b128 v[184:187], v126 offset:35840
	ds_read_b128 v[188:191], v126 offset:36864
	ds_read_b128 v[192:195], v126 offset:37888
	ds_read_b128 v[196:199], v126 offset:38912
	ds_read_b128 v[200:203], v126 offset:39936
	global_load_lds_dwordx4 v[144:145], off
	v_lshl_add_u64 v[144:145], s[18:19], 0, v[148:149]
	s_mov_b32 m0, s38
	s_nop 0
	global_load_lds_dwordx4 v[144:145], off
	s_waitcnt vmcnt(8)
	s_waitcnt lgkmcnt(0)
	s_barrier
	v_mfma_i32_16x16x64_i8 v[140:143], v[128:131], v[172:175], v[140:143]
	v_mfma_i32_16x16x64_i8 v[122:125], v[136:139], v[172:175], v[122:125]
	v_mfma_i32_16x16x64_i8 v[110:113], v[128:131], v[180:183], v[110:113]
	v_mfma_i32_16x16x64_i8 v[106:109], v[136:139], v[180:183], v[106:109]
	v_mfma_i32_16x16x64_i8 v[94:97], v[128:131], v[188:191], v[94:97]
	v_mfma_i32_16x16x64_i8 v[90:93], v[136:139], v[188:191], v[90:93]
	v_mfma_i32_16x16x64_i8 v[78:81], v[128:131], v[196:199], v[78:81]
	v_mfma_i32_16x16x64_i8 v[74:77], v[136:139], v[196:199], v[74:77]
	v_mfma_i32_16x16x64_i8 v[142:145], v[132:135], v[176:179], v[140:143]
	v_mfma_i32_16x16x64_i8 v[122:125], v[152:155], v[176:179], v[122:125]
	v_mfma_i32_16x16x64_i8 v[110:113], v[132:135], v[184:187], v[110:113]
	v_mfma_i32_16x16x64_i8 v[106:109], v[152:155], v[184:187], v[106:109]
	v_mfma_i32_16x16x64_i8 v[94:97], v[132:135], v[192:195], v[94:97]
	v_mfma_i32_16x16x64_i8 v[90:93], v[152:155], v[192:195], v[90:93]
	v_mfma_i32_16x16x64_i8 v[78:81], v[132:135], v[200:203], v[78:81]
	v_mfma_i32_16x16x64_i8 v[74:77], v[152:155], v[200:203], v[74:77]
	v_mfma_i32_16x16x64_i8 v[118:121], v[156:159], v[172:175], v[118:121]
	v_mfma_i32_16x16x64_i8 v[114:117], v[164:167], v[172:175], v[114:117]
	v_mfma_i32_16x16x64_i8 v[102:105], v[156:159], v[180:183], v[102:105]
	v_mfma_i32_16x16x64_i8 v[98:101], v[164:167], v[180:183], v[98:101]
	v_mfma_i32_16x16x64_i8 v[86:89], v[156:159], v[188:191], v[86:89]
	v_mfma_i32_16x16x64_i8 v[82:85], v[164:167], v[188:191], v[82:85]
	v_mfma_i32_16x16x64_i8 v[70:73], v[156:159], v[196:199], v[70:73]
	v_mfma_i32_16x16x64_i8 v[66:69], v[164:167], v[196:199], v[66:69]
	v_mfma_i32_16x16x64_i8 v[118:121], v[160:163], v[176:179], v[118:121]
	v_mfma_i32_16x16x64_i8 v[114:117], v[168:171], v[176:179], v[114:117]
	v_mfma_i32_16x16x64_i8 v[102:105], v[160:163], v[184:187], v[102:105]
	v_mfma_i32_16x16x64_i8 v[98:101], v[168:171], v[184:187], v[98:101]
	v_mfma_i32_16x16x64_i8 v[86:89], v[160:163], v[192:195], v[86:89]
	v_mfma_i32_16x16x64_i8 v[82:85], v[168:171], v[192:195], v[82:85]
	v_mfma_i32_16x16x64_i8 v[70:73], v[160:163], v[200:203], v[70:73]
	v_mfma_i32_16x16x64_i8 v[66:69], v[168:171], v[200:203], v[66:69]
	s_barrier
; #define PG8_STAGE(bufoff, gbase, voff) do { _Pragma("unroll") for (int _i = 0; _i < 2; ++_i) \
;         __builtin_amdgcn_global_load_lds((const unsigned*)((const char*)(gbase) + (voff)[_i]), (LAS unsigned*)(lds + (bufoff) + ldsw + _i * 8192), 16, 0, 0); } while (0)
; #define PG8_LDA(dst, b, h) do { _Pragma("unroll") for (int m = 0; m < 4; ++m) _Pragma("unroll") for (int k = 0; k < 2; ++k) dst[m][k] = *(const LAS bf16x8*)(lds + PG8_SA(b, h) + aoff + m * 2048 + k * 1024); } while (0)
; #define PG8_WAIT_V(n) asm volatile("s_waitcnt vmcnt(" #n ")" ::: "memory")
; #define PG8_WAIT_L(n) asm volatile("s_waitcnt lgkmcnt(" #n ")" ::: "memory")
; #define PG8_BAR __builtin_amdgcn_s_barrier()
; #define PG8_SCHED __builtin_amdgcn_sched_barrier(0)
; template <class Epi, class Geom, class Sched, bool ALIGN_EPI, bool I8 = false>
; __device__ __forceinline__ void gemm_phase(LAS unsigned char* lds, const Gemm g, const Sched& S, const Epi& E) {
;     ...
;             PG8_LDA(At, 1, 1); PG8_STAGE(PG8_SB(1, 0), b3, voffB); PG8_STAGE(PG8_SB(1, 1), b3 + hsB, voffB); PG8_STAGE(PG8_SA(1, 0), a3, voffA);
;             PG8_WAIT_V(8); PG8_WAIT_L(0); PG8_BAR; PG8_MMA(1, 0, At, B0); PG8_MMA(1, 1, At, B1); PG8_BAR; PG8_SCHED;
;         }
	s_mov_b32 m0, s51
	v_lshl_add_u64 v[140:141], v[204:205], 0, s[14:15]
	ds_read_b128 v[172:175], v126 offset:49152
	ds_read_b128 v[176:179], v126 offset:50176
	ds_read_b128 v[180:183], v126 offset:51200
	ds_read_b128 v[184:187], v126 offset:52224
	ds_read_b128 v[188:191], v126 offset:53248
	ds_read_b128 v[192:195], v126 offset:54272
	ds_read_b128 v[196:199], v126 offset:55296
	ds_read_b128 v[200:203], v126 offset:56320
	global_load_lds_dwordx4 v[140:141], off
	v_lshl_add_u64 v[140:141], v[206:207], 0, s[14:15]
	s_mov_b32 m0, s52
	s_nop 0
	global_load_lds_dwordx4 v[140:141], off
	v_lshl_add_u64 v[140:141], s[26:27], 0, v[146:147]
	s_mov_b32 m0, s53
	s_nop 0
	global_load_lds_dwordx4 v[140:141], off
	v_lshl_add_u64 v[140:141], s[26:27], 0, v[148:149]
	s_mov_b32 m0, s54
	s_nop 0
	global_load_lds_dwordx4 v[140:141], off
	v_lshl_add_u64 v[140:141], v[208:209], 0, s[14:15]
	s_mov_b32 m0, s39
	s_nop 0
	global_load_lds_dwordx4 v[140:141], off
	v_lshl_add_u64 v[140:141], v[210:211], 0, s[14:15]
	s_mov_b32 m0, s40
	s_nop 0
	global_load_lds_dwordx4 v[140:141], off
	s_waitcnt vmcnt(8)
	s_waitcnt lgkmcnt(0)
	s_barrier
	v_mfma_i32_16x16x64_i8 v[62:65], v[128:131], v[172:175], v[62:65]
	v_mfma_i32_16x16x64_i8 v[58:61], v[136:139], v[172:175], v[58:61]
	v_mfma_i32_16x16x64_i8 v[46:49], v[128:131], v[180:183], v[46:49]
	v_mfma_i32_16x16x64_i8 v[42:45], v[136:139], v[180:183], v[42:45]
	v_mfma_i32_16x16x64_i8 v[30:33], v[128:131], v[188:191], v[30:33]
	v_mfma_i32_16x16x64_i8 v[26:29], v[136:139], v[188:191], v[26:29]
	v_mfma_i32_16x16x64_i8 v[14:17], v[128:131], v[196:199], v[14:17]
	v_mfma_i32_16x16x64_i8 v[10:13], v[136:139], v[196:199], v[10:13]
	v_mfma_i32_16x16x64_i8 v[62:65], v[132:135], v[176:179], v[62:65]
	v_mfma_i32_16x16x64_i8 v[58:61], v[152:155], v[176:179], v[58:61]
	v_mfma_i32_16x16x64_i8 v[46:49], v[132:135], v[184:187], v[46:49]
	v_mfma_i32_16x16x64_i8 v[42:45], v[152:155], v[184:187], v[42:45]
	v_mfma_i32_16x16x64_i8 v[30:33], v[132:135], v[192:195], v[30:33]
	v_mfma_i32_16x16x64_i8 v[26:29], v[152:155], v[192:195], v[26:29]
	v_mfma_i32_16x16x64_i8 v[14:17], v[132:135], v[200:203], v[14:17]
	v_mfma_i32_16x16x64_i8 v[10:13], v[152:155], v[200:203], v[10:13]
	v_mfma_i32_16x16x64_i8 v[54:57], v[156:159], v[172:175], v[54:57]
	v_mfma_i32_16x16x64_i8 v[50:53], v[164:167], v[172:175], v[50:53]
	v_mfma_i32_16x16x64_i8 v[38:41], v[156:159], v[180:183], v[38:41]
	v_mfma_i32_16x16x64_i8 v[34:37], v[164:167], v[180:183], v[34:37]
	v_mfma_i32_16x16x64_i8 v[22:25], v[156:159], v[188:191], v[22:25]
	v_mfma_i32_16x16x64_i8 v[18:21], v[164:167], v[188:191], v[18:21]
	v_mfma_i32_16x16x64_i8 v[6:9], v[156:159], v[196:199], v[6:9]
	v_mfma_i32_16x16x64_i8 v[2:5], v[164:167], v[196:199], v[2:5]
	v_mfma_i32_16x16x64_i8 v[54:57], v[160:163], v[176:179], v[54:57]
	v_mfma_i32_16x16x64_i8 v[50:53], v[168:171], v[176:179], v[50:53]
	v_mfma_i32_16x16x64_i8 v[38:41], v[160:163], v[184:187], v[38:41]
	v_mfma_i32_16x16x64_i8 v[34:37], v[168:171], v[184:187], v[34:37]
	v_mfma_i32_16x16x64_i8 v[22:25], v[160:163], v[192:195], v[22:25]
	v_mfma_i32_16x16x64_i8 v[18:21], v[168:171], v[192:195], v[18:21]
	v_mfma_i32_16x16x64_i8 v[6:9], v[160:163], v[200:203], v[6:9]
	v_mfma_i32_16x16x64_i8 v[2:5], v[168:171], v[200:203], v[2:5]
	s_barrier
	s_andn2_b64 vcc, exec, s[16:17]
	s_mov_b64 s[18:19], -1
	s_mov_b64 s[16:17], 0
	s_movk_i32 s24, 0x100
	s_cbranch_vccz .LBB0_2243
	s_cmpk_lt_u32 s34, 0x100
	s_cbranch_scc0 .LBB0_2246
	s_barrier

; #define PG8_STAGE(bufoff, gbase, voff) do { _Pragma("unroll") for (int _i = 0; _i < 2; ++_i) \
;         __builtin_amdgcn_global_load_lds((const unsigned*)((const char*)(gbase) + (voff)[_i]), (LAS unsigned*)(lds + (bufoff) + ldsw + _i * 8192), 16, 0, 0); } while (0)
; #define PG8_LDA(dst, b, h) do { _Pragma("unroll") for (int m = 0; m < 4; ++m) _Pragma("unroll") for (int k = 0; k < 2; ++k) dst[m][k] = *(const LAS bf16x8*)(lds + PG8_SA(b, h) + aoff + m * 2048 + k * 1024); } while (0)
; #define PG8_LDB(dst, b, h) do { _Pragma("unroll") for (int n = 0; n < 2; ++n) _Pragma("unroll") for (int k = 0; k < 2; ++k) dst[n][k] = *(const LAS bf16x8*)(lds + PG8_SB(b, h) + boff + n * 2048 + k * 1024); } while (0)
; #define PG8_WAIT_V(n) asm volatile("s_waitcnt vmcnt(" #n ")" ::: "memory")
; #define PG8_WAIT_L(n) asm volatile("s_waitcnt lgkmcnt(" #n ")" ::: "memory")
; #define PG8_BAR __builtin_amdgcn_s_barrier()
; #define PG8_SCHED __builtin_amdgcn_sched_barrier(0)
; template <class Epi, class Geom, class Sched, bool ALIGN_EPI, bool I8 = false>
; __device__ __forceinline__ void gemm_phase(LAS unsigned char* lds, const Gemm g, const Sched& S, const Epi& E) {
;     ...
;             PG8_LDB(B0, 0, 0); PG8_LDB(B1, 0, 1); PG8_SCHED; PG8_LDA(At, 0, 0); PG8_STAGE(PG8_SA(1, 1), a1 + hsA, voffA);
;             PG8_WAIT_V(8); PG8_WAIT_L(0); PG8_BAR; PG8_MMA(0, 0, At, B0); PG8_MMA(0, 1, At, B1); PG8_BAR; PG8_SCHED;
;             PG8_LDA(At, 0, 1); PG8_STAGE(PG8_SB(0, 0), b2, voffB); PG8_STAGE(PG8_SB(0, 1), b2 + hsB, voffB); PG8_STAGE(PG8_SA(0, 0), a2, voffA);
;             PG8_WAIT_V(8); PG8_WAIT_L(0); PG8_BAR; PG8_MMA(1, 0, At, B0); PG8_MMA(1, 1, At, B1); PG8_BAR; PG8_SCHED;
.LBB0_2520:
	ds_read_b128 v[130:133], v248
	ds_read_b128 v[134:137], v248 offset:1024
	ds_read_b128 v[138:141], v248 offset:2048
	ds_read_b128 v[142:145], v248 offset:3072
	ds_read_b128 v[146:149], v249
	ds_read_b128 v[150:153], v249 offset:1024
	ds_read_b128 v[154:157], v249 offset:2048
	ds_read_b128 v[158:161], v249 offset:3072
	s_add_u32 s62, s20, 0xfff80080
	s_addc_u32 s63, s21, -1
	s_cmp_eq_u32 s69, 28
	s_cselect_b32 s67, s3, s63
	s_cselect_b32 s66, s33, s62
	s_cselect_b32 s63, s55, s68
	s_cselect_b32 s62, s57, s65
	v_lshl_add_u64 v[166:167], s[20:21], 0, v[182:183]
	s_add_i32 m0, s78, 0xc000
	ds_read_b128 v[162:165], v250
	ds_read_b128 v[190:193], v250 offset:1024
	ds_read_b128 v[194:197], v250 offset:2048
	ds_read_b128 v[198:201], v250 offset:3072
	ds_read_b128 v[202:205], v250 offset:4096
	ds_read_b128 v[206:209], v250 offset:5120
	ds_read_b128 v[210:213], v250 offset:6144
	ds_read_b128 v[214:217], v250 offset:7168
	global_load_lds_dwordx4 v[166:167], off
	v_lshl_add_u64 v[166:167], s[20:21], 0, v[184:185]
	s_add_i32 m0, s78, 0xe000
	s_nop 0
	global_load_lds_dwordx4 v[166:167], off
	s_waitcnt vmcnt(8)
	s_waitcnt lgkmcnt(0)
	s_barrier
	v_mfma_i32_16x16x64_i8 v[126:129], v[130:133], v[162:165], v[126:129]
	v_mfma_i32_16x16x64_i8 v[122:125], v[138:141], v[162:165], v[122:125]
	v_mfma_i32_16x16x64_i8 v[114:117], v[130:133], v[194:197], v[114:117]
	v_mfma_i32_16x16x64_i8 v[106:109], v[138:141], v[194:197], v[106:109]
	v_mfma_i32_16x16x64_i8 v[102:105], v[130:133], v[202:205], v[102:105]
	v_mfma_i32_16x16x64_i8 v[94:97], v[138:141], v[202:205], v[94:97]
	v_mfma_i32_16x16x64_i8 v[86:89], v[130:133], v[210:213], v[86:89]
	v_mfma_i32_16x16x64_i8 v[78:81], v[138:141], v[210:213], v[78:81]
	v_mfma_i32_16x16x64_i8 v[126:129], v[134:137], v[190:193], v[126:129]
	v_mfma_i32_16x16x64_i8 v[122:125], v[142:145], v[190:193], v[122:125]
	v_mfma_i32_16x16x64_i8 v[114:117], v[134:137], v[198:201], v[114:117]
	v_mfma_i32_16x16x64_i8 v[106:109], v[142:145], v[198:201], v[106:109]
	v_mfma_i32_16x16x64_i8 v[102:105], v[134:137], v[206:209], v[102:105]
	v_mfma_i32_16x16x64_i8 v[94:97], v[142:145], v[206:209], v[94:97]
	v_mfma_i32_16x16x64_i8 v[86:89], v[134:137], v[214:217], v[86:89]
	v_mfma_i32_16x16x64_i8 v[78:81], v[142:145], v[214:217], v[78:81]
	v_mfma_i32_16x16x64_i8 v[118:121], v[146:149], v[162:165], v[118:121]
	v_mfma_i32_16x16x64_i8 v[82:85], v[154:157], v[162:165], v[82:85]
	v_mfma_i32_16x16x64_i8 v[110:113], v[146:149], v[194:197], v[110:113]
	v_mfma_i32_16x16x64_i8 v[74:77], v[154:157], v[194:197], v[74:77]
	v_mfma_i32_16x16x64_i8 v[98:101], v[146:149], v[202:205], v[98:101]
	v_mfma_i32_16x16x64_i8 v[66:69], v[154:157], v[202:205], v[66:69]
	v_mfma_i32_16x16x64_i8 v[90:93], v[146:149], v[210:213], v[90:93]
	v_mfma_i32_16x16x64_i8 v[58:61], v[154:157], v[210:213], v[58:61]
	v_mfma_i32_16x16x64_i8 v[118:121], v[150:153], v[190:193], v[118:121]
	v_mfma_i32_16x16x64_i8 v[82:85], v[158:161], v[190:193], v[82:85]
	v_mfma_i32_16x16x64_i8 v[110:113], v[150:153], v[198:201], v[110:113]
	v_mfma_i32_16x16x64_i8 v[74:77], v[158:161], v[198:201], v[74:77]
	v_mfma_i32_16x16x64_i8 v[98:101], v[150:153], v[206:209], v[98:101]
	v_mfma_i32_16x16x64_i8 v[66:69], v[158:161], v[206:209], v[66:69]
	v_mfma_i32_16x16x64_i8 v[90:93], v[150:153], v[214:217], v[90:93]
	v_mfma_i32_16x16x64_i8 v[58:61], v[158:161], v[214:217], v[58:61]
	s_barrier
	s_add_i32 s70, s92, s77
	v_lshl_add_u64 v[166:167], s[62:63], 0, v[170:171]
	s_mov_b32 m0, s70
	ds_read_b128 v[162:165], v250 offset:16384
	ds_read_b128 v[190:193], v250 offset:17408
	ds_read_b128 v[194:197], v250 offset:18432
	ds_read_b128 v[198:201], v250 offset:19456
	ds_read_b128 v[202:205], v250 offset:20480
	ds_read_b128 v[206:209], v250 offset:21504
	ds_read_b128 v[210:213], v250 offset:22528
	ds_read_b128 v[214:217], v250 offset:23552
	global_load_lds_dwordx4 v[166:167], off
	s_add_i32 m0, s70, 0x2000
	s_add_u32 s70, s62, 0x80000
	v_lshl_add_u64 v[218:219], s[62:63], 0, v[174:175]
	s_addc_u32 s71, s63, 0
	s_add_i32 s72, s93, s77
	global_load_lds_dwordx4 v[218:219], off
	v_lshl_add_u64 v[220:221], s[70:71], 0, v[170:171]
	s_mov_b32 m0, s72
	v_lshl_add_u64 v[222:223], s[66:67], 0, v[172:173]
	global_load_lds_dwordx4 v[220:221], off
	v_lshl_add_u64 v[220:221], s[70:71], 0, v[174:175]
	s_add_i32 m0, s72, 0x2000
	s_nop 0
	global_load_lds_dwordx4 v[220:221], off
	v_lshl_add_u64 v[220:221], s[66:67], 0, v[168:169]
	s_mov_b32 m0, s78
	s_nop 0
	global_load_lds_dwordx4 v[220:221], off
	s_mov_b32 m0, s79
	s_nop 0
	global_load_lds_dwordx4 v[222:223], off
	s_waitcnt vmcnt(8)
	s_waitcnt lgkmcnt(0)
	s_barrier
; #define PG8_STAGE(bufoff, gbase, voff) do { _Pragma("unroll") for (int _i = 0; _i < 2; ++_i) \
;         __builtin_amdgcn_global_load_lds((const unsigned*)((const char*)(gbase) + (voff)[_i]), (LAS unsigned*)(lds + (bufoff) + ldsw + _i * 8192), 16, 0, 0); } while (0)
; #define PG8_LDA(dst, b, h) do { _Pragma("unroll") for (int m = 0; m < 4; ++m) _Pragma("unroll") for (int k = 0; k < 2; ++k) dst[m][k] = *(const LAS bf16x8*)(lds + PG8_SA(b, h) + aoff + m * 2048 + k * 1024); } while (0)
; #define PG8_LDB(dst, b, h) do { _Pragma("unroll") for (int n = 0; n < 2; ++n) _Pragma("unroll") for (int k = 0; k < 2; ++k) dst[n][k] = *(const LAS bf16x8*)(lds + PG8_SB(b, h) + boff + n * 2048 + k * 1024); } while (0)
; #define PG8_WAIT_V(n) asm volatile("s_waitcnt vmcnt(" #n ")" ::: "memory")
; #define PG8_WAIT_L(n) asm volatile("s_waitcnt lgkmcnt(" #n ")" ::: "memory")
; #define PG8_BAR __builtin_amdgcn_s_barrier()
; #define PG8_SCHED __builtin_amdgcn_sched_barrier(0)
; template <class Epi, class Geom, class Sched, bool ALIGN_EPI, bool I8 = false>
; __device__ __forceinline__ void gemm_phase(LAS unsigned char* lds, const Gemm g, const Sched& S, const Epi& E) {
;     ...
;             PG8_WAIT_V(8); PG8_WAIT_L(0); PG8_BAR; PG8_MMA(1, 0, At, B0); PG8_MMA(1, 1, At, B1); PG8_BAR; PG8_SCHED;
;             PG8_LDB(B0, 1, 0); PG8_LDB(B1, 1, 1); PG8_SCHED; PG8_LDA(At, 1, 0); PG8_STAGE(PG8_SA(0, 1), a2 + hsA, voffA);
;             PG8_WAIT_V(8); PG8_WAIT_L(0); PG8_BAR; PG8_MMA(0, 0, At, B0); PG8_MMA(0, 1, At, B1); PG8_BAR; PG8_SCHED;
	v_mfma_i32_16x16x64_i8 v[70:73], v[130:133], v[162:165], v[70:73]
	v_mfma_i32_16x16x64_i8 v[62:65], v[138:141], v[162:165], v[62:65]
	v_mfma_i32_16x16x64_i8 v[38:41], v[130:133], v[194:197], v[38:41]
	v_mfma_i32_16x16x64_i8 v[54:57], v[138:141], v[194:197], v[54:57]
	v_mfma_i32_16x16x64_i8 v[30:33], v[130:133], v[202:205], v[30:33]
	v_mfma_i32_16x16x64_i8 v[50:53], v[138:141], v[202:205], v[50:53]
	v_mfma_i32_16x16x64_i8 v[26:29], v[130:133], v[210:213], v[26:29]
	v_mfma_i32_16x16x64_i8 v[18:21], v[138:141], v[210:213], v[18:21]
	v_mfma_i32_16x16x64_i8 v[70:73], v[134:137], v[190:193], v[70:73]
	v_mfma_i32_16x16x64_i8 v[62:65], v[142:145], v[190:193], v[62:65]
	v_mfma_i32_16x16x64_i8 v[38:41], v[134:137], v[198:201], v[38:41]
	v_mfma_i32_16x16x64_i8 v[54:57], v[142:145], v[198:201], v[54:57]
	v_mfma_i32_16x16x64_i8 v[30:33], v[134:137], v[206:209], v[30:33]
	v_mfma_i32_16x16x64_i8 v[50:53], v[142:145], v[206:209], v[50:53]
	v_mfma_i32_16x16x64_i8 v[26:29], v[134:137], v[214:217], v[26:29]
	v_mfma_i32_16x16x64_i8 v[18:21], v[142:145], v[214:217], v[18:21]
	v_mfma_i32_16x16x64_i8 v[46:49], v[146:149], v[162:165], v[46:49]
	v_mfma_i32_16x16x64_i8 v[14:17], v[154:157], v[162:165], v[14:17]
	v_mfma_i32_16x16x64_i8 v[42:45], v[146:149], v[194:197], v[42:45]
	v_mfma_i32_16x16x64_i8 v[10:13], v[154:157], v[194:197], v[10:13]
	v_mfma_i32_16x16x64_i8 v[34:37], v[146:149], v[202:205], v[34:37]
	v_mfma_i32_16x16x64_i8 v[6:9], v[154:157], v[202:205], v[6:9]
	v_mfma_i32_16x16x64_i8 v[22:25], v[146:149], v[210:213], v[22:25]
	v_mfma_i32_16x16x64_i8 v[2:5], v[154:157], v[210:213], v[2:5]
	v_mfma_i32_16x16x64_i8 v[46:49], v[150:153], v[190:193], v[46:49]
	v_mfma_i32_16x16x64_i8 v[14:17], v[158:161], v[190:193], v[14:17]
	v_mfma_i32_16x16x64_i8 v[42:45], v[150:153], v[198:201], v[42:45]
	v_mfma_i32_16x16x64_i8 v[10:13], v[158:161], v[198:201], v[10:13]
	v_mfma_i32_16x16x64_i8 v[34:37], v[150:153], v[206:209], v[34:37]
	v_mfma_i32_16x16x64_i8 v[6:9], v[158:161], v[206:209], v[6:9]
	v_mfma_i32_16x16x64_i8 v[22:25], v[150:153], v[214:217], v[22:25]
	v_mfma_i32_16x16x64_i8 v[2:5], v[158:161], v[214:217], v[2:5]
	s_barrier
	s_add_i32 s70, 0, 0x18000
	s_add_i32 s71, 0, 0x1c000
	v_add_u32_e32 v142, s70, v1
	v_add_u32_e32 v158, s71, v1
	ds_read_b128 v[130:133], v142
	ds_read_b128 v[134:137], v142 offset:1024
	ds_read_b128 v[138:141], v142 offset:2048
	ds_read_b128 v[142:145], v142 offset:3072
	ds_read_b128 v[146:149], v158
	ds_read_b128 v[150:153], v158 offset:1024
	ds_read_b128 v[154:157], v158 offset:2048
	ds_read_b128 v[158:161], v158 offset:3072
	s_add_u32 s66, s66, 0x80000
	s_addc_u32 s67, s67, 0
	s_mov_b32 m0, s80
	v_lshl_add_u64 v[224:225], s[66:67], 0, v[168:169]
	ds_read_b128 v[162:165], v250 offset:32768
	ds_read_b128 v[190:193], v250 offset:33792
	ds_read_b128 v[194:197], v250 offset:34816
	ds_read_b128 v[198:201], v250 offset:35840
	ds_read_b128 v[202:205], v250 offset:36864
	ds_read_b128 v[206:209], v250 offset:37888
	ds_read_b128 v[210:213], v250 offset:38912
	ds_read_b128 v[214:217], v250 offset:39936
	global_load_lds_dwordx4 v[224:225], off
	v_lshl_add_u64 v[224:225], s[66:67], 0, v[172:173]
	s_mov_b32 m0, s81
	s_nop 0
	global_load_lds_dwordx4 v[224:225], off
	s_waitcnt vmcnt(8)
	s_waitcnt lgkmcnt(0)
	s_barrier
	v_mfma_i32_16x16x64_i8 v[126:129], v[130:133], v[162:165], v[126:129]
	v_mfma_i32_16x16x64_i8 v[122:125], v[138:141], v[162:165], v[122:125]
	v_mfma_i32_16x16x64_i8 v[114:117], v[130:133], v[194:197], v[114:117]
	v_mfma_i32_16x16x64_i8 v[106:109], v[138:141], v[194:197], v[106:109]
	v_mfma_i32_16x16x64_i8 v[102:105], v[130:133], v[202:205], v[102:105]
	v_mfma_i32_16x16x64_i8 v[94:97], v[138:141], v[202:205], v[94:97]
	v_mfma_i32_16x16x64_i8 v[86:89], v[130:133], v[210:213], v[86:89]
	v_mfma_i32_16x16x64_i8 v[78:81], v[138:141], v[210:213], v[78:81]
	v_mfma_i32_16x16x64_i8 v[126:129], v[134:137], v[190:193], v[126:129]
	v_mfma_i32_16x16x64_i8 v[122:125], v[142:145], v[190:193], v[122:125]
	v_mfma_i32_16x16x64_i8 v[114:117], v[134:137], v[198:201], v[114:117]
	v_mfma_i32_16x16x64_i8 v[106:109], v[142:145], v[198:201], v[106:109]
	v_mfma_i32_16x16x64_i8 v[102:105], v[134:137], v[206:209], v[102:105]
	v_mfma_i32_16x16x64_i8 v[94:97], v[142:145], v[206:209], v[94:97]
	v_mfma_i32_16x16x64_i8 v[86:89], v[134:137], v[214:217], v[86:89]
	v_mfma_i32_16x16x64_i8 v[78:81], v[142:145], v[214:217], v[78:81]
	v_mfma_i32_16x16x64_i8 v[118:121], v[146:149], v[162:165], v[118:121]
	v_mfma_i32_16x16x64_i8 v[82:85], v[154:157], v[162:165], v[82:85]
	v_mfma_i32_16x16x64_i8 v[110:113], v[146:149], v[194:197], v[110:113]
	v_mfma_i32_16x16x64_i8 v[74:77], v[154:157], v[194:197], v[74:77]
	v_mfma_i32_16x16x64_i8 v[98:101], v[146:149], v[202:205], v[98:101]
	v_mfma_i32_16x16x64_i8 v[66:69], v[154:157], v[202:205], v[66:69]
	v_mfma_i32_16x16x64_i8 v[90:93], v[146:149], v[210:213], v[90:93]
	v_mfma_i32_16x16x64_i8 v[58:61], v[154:157], v[210:213], v[58:61]
	v_mfma_i32_16x16x64_i8 v[118:121], v[150:153], v[190:193], v[118:121]
	v_mfma_i32_16x16x64_i8 v[82:85], v[158:161], v[190:193], v[82:85]
	v_mfma_i32_16x16x64_i8 v[110:113], v[150:153], v[198:201], v[110:113]
	v_mfma_i32_16x16x64_i8 v[74:77], v[158:161], v[198:201], v[74:77]
	v_mfma_i32_16x16x64_i8 v[98:101], v[150:153], v[206:209], v[98:101]
	v_mfma_i32_16x16x64_i8 v[66:69], v[158:161], v[206:209], v[66:69]
	v_mfma_i32_16x16x64_i8 v[90:93], v[150:153], v[214:217], v[90:93]
	v_mfma_i32_16x16x64_i8 v[58:61], v[158:161], v[214:217], v[58:61]
	s_barrier
; #define PG8_STAGE(bufoff, gbase, voff) do { _Pragma("unroll") for (int _i = 0; _i < 2; ++_i) \
;         __builtin_amdgcn_global_load_lds((const unsigned*)((const char*)(gbase) + (voff)[_i]), (LAS unsigned*)(lds + (bufoff) + ldsw + _i * 8192), 16, 0, 0); } while (0)
; #define PG8_LDA(dst, b, h) do { _Pragma("unroll") for (int m = 0; m < 4; ++m) _Pragma("unroll") for (int k = 0; k < 2; ++k) dst[m][k] = *(const LAS bf16x8*)(lds + PG8_SA(b, h) + aoff + m * 2048 + k * 1024); } while (0)
; #define PG8_WAIT_V(n) asm volatile("s_waitcnt vmcnt(" #n ")" ::: "memory")
; #define PG8_WAIT_L(n) asm volatile("s_waitcnt lgkmcnt(" #n ")" ::: "memory")
; #define PG8_BAR __builtin_amdgcn_s_barrier()
; #define PG8_SCHED __builtin_amdgcn_sched_barrier(0)
; template <class Epi, class Geom, class Sched, bool ALIGN_EPI, bool I8 = false>
; __device__ __forceinline__ void gemm_phase(LAS unsigned char* lds, const Gemm g, const Sched& S, const Epi& E) {
;     ...
;             PG8_LDA(At, 1, 1); PG8_STAGE(PG8_SB(1, 0), b3, voffB); PG8_STAGE(PG8_SB(1, 1), b3 + hsB, voffB); PG8_STAGE(PG8_SA(1, 0), a3, voffA);
;             PG8_WAIT_V(8); PG8_WAIT_L(0); PG8_BAR; PG8_MMA(1, 0, At, B0); PG8_MMA(1, 1, At, B1); PG8_BAR; PG8_SCHED;
;         }
	s_add_i32 s66, s70, s77
	v_lshl_add_u64 v[166:167], v[166:167], 0, s[28:29]
	s_mov_b32 m0, s66
	ds_read_b128 v[162:165], v250 offset:49152
	ds_read_b128 v[190:193], v250 offset:50176
	ds_read_b128 v[194:197], v250 offset:51200
	ds_read_b128 v[198:201], v250 offset:52224
	ds_read_b128 v[202:205], v250 offset:53248
	ds_read_b128 v[206:209], v250 offset:54272
	ds_read_b128 v[210:213], v250 offset:55296
	ds_read_b128 v[214:217], v250 offset:56320
	global_load_lds_dwordx4 v[166:167], off
	s_add_i32 m0, s66, 0x2000
	s_add_u32 s62, s62, 0x80080
	v_lshl_add_u64 v[166:167], v[218:219], 0, s[28:29]
	s_addc_u32 s63, s63, 0
	s_add_i32 s66, s71, s77
	global_load_lds_dwordx4 v[166:167], off
	v_lshl_add_u64 v[166:167], s[62:63], 0, v[170:171]
	s_mov_b32 m0, s66
	s_nop 0
	global_load_lds_dwordx4 v[166:167], off
	v_lshl_add_u64 v[166:167], s[62:63], 0, v[174:175]
	s_add_i32 m0, s66, 0x2000
	s_nop 0
	global_load_lds_dwordx4 v[166:167], off
	v_lshl_add_u64 v[166:167], v[220:221], 0, s[28:29]
	s_mov_b32 m0, s88
	s_nop 0
	global_load_lds_dwordx4 v[166:167], off
	v_lshl_add_u64 v[166:167], v[222:223], 0, s[28:29]
	s_mov_b32 m0, s89
	s_nop 0
	global_load_lds_dwordx4 v[166:167], off
	s_waitcnt vmcnt(8)
	s_waitcnt lgkmcnt(0)
	s_barrier
	v_mfma_i32_16x16x64_i8 v[70:73], v[130:133], v[162:165], v[70:73]
	v_mfma_i32_16x16x64_i8 v[62:65], v[138:141], v[162:165], v[62:65]
	v_mfma_i32_16x16x64_i8 v[38:41], v[130:133], v[194:197], v[38:41]
	v_mfma_i32_16x16x64_i8 v[54:57], v[138:141], v[194:197], v[54:57]
	v_mfma_i32_16x16x64_i8 v[30:33], v[130:133], v[202:205], v[30:33]
	v_mfma_i32_16x16x64_i8 v[50:53], v[138:141], v[202:205], v[50:53]
	v_mfma_i32_16x16x64_i8 v[26:29], v[130:133], v[210:213], v[26:29]
	v_mfma_i32_16x16x64_i8 v[18:21], v[138:141], v[210:213], v[18:21]
	v_mfma_i32_16x16x64_i8 v[70:73], v[134:137], v[190:193], v[70:73]
	v_mfma_i32_16x16x64_i8 v[62:65], v[142:145], v[190:193], v[62:65]
	v_mfma_i32_16x16x64_i8 v[38:41], v[134:137], v[198:201], v[38:41]
	v_mfma_i32_16x16x64_i8 v[54:57], v[142:145], v[198:201], v[54:57]
	v_mfma_i32_16x16x64_i8 v[30:33], v[134:137], v[206:209], v[30:33]
	v_mfma_i32_16x16x64_i8 v[50:53], v[142:145], v[206:209], v[50:53]
	v_mfma_i32_16x16x64_i8 v[26:29], v[134:137], v[214:217], v[26:29]
	v_mfma_i32_16x16x64_i8 v[18:21], v[142:145], v[214:217], v[18:21]
	v_mfma_i32_16x16x64_i8 v[46:49], v[146:149], v[162:165], v[46:49]
	v_mfma_i32_16x16x64_i8 v[14:17], v[154:157], v[162:165], v[14:17]
	v_mfma_i32_16x16x64_i8 v[42:45], v[146:149], v[194:197], v[42:45]
	v_mfma_i32_16x16x64_i8 v[10:13], v[154:157], v[194:197], v[10:13]
	v_mfma_i32_16x16x64_i8 v[34:37], v[146:149], v[202:205], v[34:37]
	v_mfma_i32_16x16x64_i8 v[6:9], v[154:157], v[202:205], v[6:9]
	v_mfma_i32_16x16x64_i8 v[22:25], v[146:149], v[210:213], v[22:25]
	v_mfma_i32_16x16x64_i8 v[2:5], v[154:157], v[210:213], v[2:5]
	v_mfma_i32_16x16x64_i8 v[46:49], v[150:153], v[190:193], v[46:49]
	v_mfma_i32_16x16x64_i8 v[14:17], v[158:161], v[190:193], v[14:17]
	v_mfma_i32_16x16x64_i8 v[42:45], v[150:153], v[198:201], v[42:45]
	v_mfma_i32_16x16x64_i8 v[10:13], v[158:161], v[198:201], v[10:13]
	v_mfma_i32_16x16x64_i8 v[34:37], v[150:153], v[206:209], v[34:37]
	v_mfma_i32_16x16x64_i8 v[6:9], v[158:161], v[206:209], v[6:9]
	v_mfma_i32_16x16x64_i8 v[22:25], v[150:153], v[214:217], v[22:25]
	v_mfma_i32_16x16x64_i8 v[2:5], v[158:161], v[214:217], v[2:5]
	s_barrier
	s_add_i32 s69, s69, 2
	s_add_u32 s20, s20, 0x100
	s_addc_u32 s21, s21, 0
	s_add_u32 s65, s65, 0x100
	s_addc_u32 s68, s68, 0
	s_cmp_gt_u32 s69, 29
	s_cbranch_scc0 .LBB0_2520
	s_and_b64 vcc, exec, s[30:31]
	s_cbranch_vccz .LBB0_2523
	s_barrier

; #define PG8_STAGE(bufoff, gbase, voff) do { _Pragma("unroll") for (int _i = 0; _i < 2; ++_i) \
;         __builtin_amdgcn_global_load_lds((const unsigned*)((const char*)(gbase) + (voff)[_i]), (LAS unsigned*)(lds + (bufoff) + ldsw + _i * 8192), 16, 0, 0); } while (0)
; #define PG8_LDA(dst, b, h) do { _Pragma("unroll") for (int m = 0; m < 4; ++m) _Pragma("unroll") for (int k = 0; k < 2; ++k) dst[m][k] = *(const LAS bf16x8*)(lds + PG8_SA(b, h) + aoff + m * 2048 + k * 1024); } while (0)
; #define PG8_LDB(dst, b, h) do { _Pragma("unroll") for (int n = 0; n < 2; ++n) _Pragma("unroll") for (int k = 0; k < 2; ++k) dst[n][k] = *(const LAS bf16x8*)(lds + PG8_SB(b, h) + boff + n * 2048 + k * 1024); } while (0)
; #define PG8_WAIT_V(n) asm volatile("s_waitcnt vmcnt(" #n ")" ::: "memory")
; #define PG8_WAIT_L(n) asm volatile("s_waitcnt lgkmcnt(" #n ")" ::: "memory")
; #define PG8_BAR __builtin_amdgcn_s_barrier()
; #define PG8_SCHED __builtin_amdgcn_sched_barrier(0)
; template <class Epi, class Geom, class Sched, bool ALIGN_EPI, bool I8 = false>
; __device__ __forceinline__ void gemm_phase(LAS unsigned char* lds, const Gemm g, const Sched& S, const Epi& E) {
;     ...
;             PG8_LDB(B0, 0, 0); PG8_LDB(B1, 0, 1); PG8_SCHED; PG8_LDA(At, 0, 0); PG8_STAGE(PG8_SA(1, 1), a1 + hsA, voffA);
;             PG8_WAIT_V(8); PG8_WAIT_L(0); PG8_BAR; PG8_MMA(0, 0, At, B0); PG8_MMA(0, 1, At, B1); PG8_BAR; PG8_SCHED;
;             PG8_LDA(At, 0, 1); PG8_STAGE(PG8_SB(0, 0), b2, voffB); PG8_STAGE(PG8_SB(0, 1), b2 + hsB, voffB); PG8_STAGE(PG8_SA(0, 0), a2, voffA);
;             PG8_WAIT_V(8); PG8_WAIT_L(0); PG8_BAR; PG8_MMA(1, 0, At, B0); PG8_MMA(1, 1, At, B1); PG8_BAR; PG8_SCHED;
.LBB0_2872:
	ds_read_b128 v[90:93], v181
	ds_read_b128 v[98:101], v181 offset:1024
	ds_read_b128 v[102:105], v181 offset:2048
	ds_read_b128 v[160:163], v181 offset:3072
	ds_read_b128 v[182:185], v206
	ds_read_b128 v[186:189], v206 offset:1024
	ds_read_b128 v[190:193], v206 offset:2048
	ds_read_b128 v[194:197], v206 offset:3072
	s_add_u32 s38, s36, 0xffe80080
	s_addc_u32 s39, s37, -1
	s_cmpk_eq_i32 s62, 0x5c
	s_cselect_b32 s41, s1, s39
	s_cselect_b32 s40, s0, s38
	s_cselect_b32 s39, s35, s61
	s_cselect_b32 s38, s34, s60
	v_lshl_add_u64 v[152:153], s[36:37], 0, v[146:147]
	s_add_i32 m0, s33, 0xc000
	ds_read_b128 v[198:201], v207
	ds_read_b128 v[202:205], v207 offset:1024
	ds_read_b128 v[208:211], v207 offset:2048
	ds_read_b128 v[212:215], v207 offset:3072
	ds_read_b128 v[216:219], v207 offset:4096
	ds_read_b128 v[220:223], v207 offset:5120
	ds_read_b128 v[224:227], v207 offset:6144
	ds_read_b128 v[228:231], v207 offset:7168
	global_load_lds_dwordx4 v[152:153], off
	v_lshl_add_u64 v[152:153], s[36:37], 0, v[148:149]
	s_add_i32 m0, s33, 0xe000
	s_nop 0
	global_load_lds_dwordx4 v[152:153], off
	s_waitcnt vmcnt(8)
	s_waitcnt lgkmcnt(0)
	s_barrier
	v_mfma_i32_16x16x64_i8 v[94:97], v[90:93], v[198:201], v[94:97]
	v_mfma_i32_16x16x64_i8 v[138:141], v[102:105], v[198:201], v[138:141]
	v_mfma_i32_16x16x64_i8 v[130:133], v[90:93], v[208:211], v[130:133]
	v_mfma_i32_16x16x64_i8 v[122:125], v[102:105], v[208:211], v[122:125]
	v_mfma_i32_16x16x64_i8 v[110:113], v[90:93], v[216:219], v[110:113]
	v_mfma_i32_16x16x64_i8 v[106:109], v[102:105], v[216:219], v[106:109]
	v_mfma_i32_16x16x64_i8 v[82:85], v[90:93], v[224:227], v[82:85]
	v_mfma_i32_16x16x64_i8 v[74:77], v[102:105], v[224:227], v[74:77]
	v_mfma_i32_16x16x64_i8 v[94:97], v[98:101], v[202:205], v[94:97]
	v_mfma_i32_16x16x64_i8 v[138:141], v[160:163], v[202:205], v[138:141]
	v_mfma_i32_16x16x64_i8 v[130:133], v[98:101], v[212:215], v[130:133]
	v_mfma_i32_16x16x64_i8 v[122:125], v[160:163], v[212:215], v[122:125]
	v_mfma_i32_16x16x64_i8 v[110:113], v[98:101], v[220:223], v[110:113]
	v_mfma_i32_16x16x64_i8 v[106:109], v[160:163], v[220:223], v[106:109]
	v_mfma_i32_16x16x64_i8 v[82:85], v[98:101], v[228:231], v[82:85]
	v_mfma_i32_16x16x64_i8 v[74:77], v[160:163], v[228:231], v[74:77]
	v_mfma_i32_16x16x64_i8 v[134:137], v[182:185], v[198:201], v[134:137]
	v_mfma_i32_16x16x64_i8 v[126:129], v[190:193], v[198:201], v[126:129]
	v_mfma_i32_16x16x64_i8 v[118:121], v[182:185], v[208:211], v[118:121]
	v_mfma_i32_16x16x64_i8 v[114:117], v[190:193], v[208:211], v[114:117]
	v_mfma_i32_16x16x64_i8 v[86:89], v[182:185], v[216:219], v[86:89]
	v_mfma_i32_16x16x64_i8 v[78:81], v[190:193], v[216:219], v[78:81]
	v_mfma_i32_16x16x64_i8 v[70:73], v[182:185], v[224:227], v[70:73]
	v_mfma_i32_16x16x64_i8 v[66:69], v[190:193], v[224:227], v[66:69]
	v_mfma_i32_16x16x64_i8 v[134:137], v[186:189], v[202:205], v[134:137]
	v_mfma_i32_16x16x64_i8 v[126:129], v[194:197], v[202:205], v[126:129]
	v_mfma_i32_16x16x64_i8 v[118:121], v[186:189], v[212:215], v[118:121]
	v_mfma_i32_16x16x64_i8 v[114:117], v[194:197], v[212:215], v[114:117]
	v_mfma_i32_16x16x64_i8 v[86:89], v[186:189], v[220:223], v[86:89]
	v_mfma_i32_16x16x64_i8 v[78:81], v[194:197], v[220:223], v[78:81]
	v_mfma_i32_16x16x64_i8 v[70:73], v[186:189], v[228:231], v[70:73]
	v_mfma_i32_16x16x64_i8 v[66:69], v[194:197], v[228:231], v[66:69]
	s_barrier
	s_add_i32 s63, s14, s46
	v_lshl_add_u64 v[152:153], s[38:39], 0, v[144:145]
	s_mov_b32 m0, s63
	ds_read_b128 v[198:201], v207 offset:16384
	ds_read_b128 v[202:205], v207 offset:17408
	ds_read_b128 v[208:211], v207 offset:18432
	ds_read_b128 v[212:215], v207 offset:19456
	ds_read_b128 v[216:219], v207 offset:20480
	ds_read_b128 v[220:223], v207 offset:21504
	ds_read_b128 v[224:227], v207 offset:22528
	ds_read_b128 v[228:231], v207 offset:23552
	global_load_lds_dwordx4 v[152:153], off
	s_add_i32 m0, s63, 0x2000
	s_add_u32 s64, s38, 0x180000
	v_lshl_add_u64 v[156:157], s[38:39], 0, v[142:143]
	s_addc_u32 s65, s39, 0
	s_add_i32 s63, s55, s46
	global_load_lds_dwordx4 v[156:157], off
	v_lshl_add_u64 v[166:167], s[64:65], 0, v[144:145]
	s_mov_b32 m0, s63
	v_lshl_add_u64 v[170:171], s[40:41], 0, v[142:143]
	global_load_lds_dwordx4 v[166:167], off
	v_lshl_add_u64 v[166:167], s[64:65], 0, v[142:143]
	s_add_i32 m0, s63, 0x2000
	s_nop 0
	global_load_lds_dwordx4 v[166:167], off
	v_lshl_add_u64 v[166:167], s[40:41], 0, v[144:145]
	s_mov_b32 m0, s33
	s_nop 0
	global_load_lds_dwordx4 v[166:167], off
	s_mov_b32 m0, s49
	s_nop 0
	global_load_lds_dwordx4 v[170:171], off
	s_waitcnt vmcnt(8)
	s_waitcnt lgkmcnt(0)
	s_barrier
; #define PG8_STAGE(bufoff, gbase, voff) do { _Pragma("unroll") for (int _i = 0; _i < 2; ++_i) \
;         __builtin_amdgcn_global_load_lds((const unsigned*)((const char*)(gbase) + (voff)[_i]), (LAS unsigned*)(lds + (bufoff) + ldsw + _i * 8192), 16, 0, 0); } while (0)
; #define PG8_LDA(dst, b, h) do { _Pragma("unroll") for (int m = 0; m < 4; ++m) _Pragma("unroll") for (int k = 0; k < 2; ++k) dst[m][k] = *(const LAS bf16x8*)(lds + PG8_SA(b, h) + aoff + m * 2048 + k * 1024); } while (0)
; #define PG8_LDB(dst, b, h) do { _Pragma("unroll") for (int n = 0; n < 2; ++n) _Pragma("unroll") for (int k = 0; k < 2; ++k) dst[n][k] = *(const LAS bf16x8*)(lds + PG8_SB(b, h) + boff + n * 2048 + k * 1024); } while (0)
; #define PG8_WAIT_V(n) asm volatile("s_waitcnt vmcnt(" #n ")" ::: "memory")
; #define PG8_WAIT_L(n) asm volatile("s_waitcnt lgkmcnt(" #n ")" ::: "memory")
; #define PG8_BAR __builtin_amdgcn_s_barrier()
; #define PG8_SCHED __builtin_amdgcn_sched_barrier(0)
; template <class Epi, class Geom, class Sched, bool ALIGN_EPI, bool I8 = false>
; __device__ __forceinline__ void gemm_phase(LAS unsigned char* lds, const Gemm g, const Sched& S, const Epi& E) {
;     ...
;             PG8_WAIT_V(8); PG8_WAIT_L(0); PG8_BAR; PG8_MMA(0, 0, At, B0); PG8_MMA(0, 1, At, B1); PG8_BAR; PG8_SCHED;
;             PG8_LDA(At, 0, 1); PG8_STAGE(PG8_SB(0, 0), b2, voffB); PG8_STAGE(PG8_SB(0, 1), b2 + hsB, voffB); PG8_STAGE(PG8_SA(0, 0), a2, voffA);
;             PG8_WAIT_V(8); PG8_WAIT_L(0); PG8_BAR; PG8_MMA(1, 0, At, B0); PG8_MMA(1, 1, At, B1); PG8_BAR; PG8_SCHED;
;             PG8_LDB(B0, 1, 0); PG8_LDB(B1, 1, 1); PG8_SCHED; PG8_LDA(At, 1, 0); PG8_STAGE(PG8_SA(0, 1), a2 + hsA, voffA);
;             PG8_WAIT_V(8); PG8_WAIT_L(0); PG8_BAR; PG8_MMA(0, 0, At, B0); PG8_MMA(0, 1, At, B1); PG8_BAR; PG8_SCHED;
	v_mfma_i32_16x16x64_i8 v[62:65], v[90:93], v[198:201], v[62:65]
	v_mfma_i32_16x16x64_i8 v[58:61], v[102:105], v[198:201], v[58:61]
	v_mfma_i32_16x16x64_i8 v[50:53], v[90:93], v[208:211], v[50:53]
	v_mfma_i32_16x16x64_i8 v[42:45], v[102:105], v[208:211], v[42:45]
	v_mfma_i32_16x16x64_i8 v[30:33], v[90:93], v[216:219], v[30:33]
	v_mfma_i32_16x16x64_i8 v[26:29], v[102:105], v[216:219], v[26:29]
	v_mfma_i32_16x16x64_i8 v[18:21], v[90:93], v[224:227], v[18:21]
	v_mfma_i32_16x16x64_i8 v[10:13], v[102:105], v[224:227], v[10:13]
	v_mfma_i32_16x16x64_i8 v[62:65], v[98:101], v[202:205], v[62:65]
	v_mfma_i32_16x16x64_i8 v[58:61], v[160:163], v[202:205], v[58:61]
	v_mfma_i32_16x16x64_i8 v[50:53], v[98:101], v[212:215], v[50:53]
	v_mfma_i32_16x16x64_i8 v[42:45], v[160:163], v[212:215], v[42:45]
	v_mfma_i32_16x16x64_i8 v[30:33], v[98:101], v[220:223], v[30:33]
	v_mfma_i32_16x16x64_i8 v[26:29], v[160:163], v[220:223], v[26:29]
	v_mfma_i32_16x16x64_i8 v[18:21], v[98:101], v[228:231], v[18:21]
	v_mfma_i32_16x16x64_i8 v[10:13], v[160:163], v[228:231], v[10:13]
	v_mfma_i32_16x16x64_i8 v[54:57], v[182:185], v[198:201], v[54:57]
	v_mfma_i32_16x16x64_i8 v[46:49], v[190:193], v[198:201], v[46:49]
	v_mfma_i32_16x16x64_i8 v[38:41], v[182:185], v[208:211], v[38:41]
	v_mfma_i32_16x16x64_i8 v[34:37], v[190:193], v[208:211], v[34:37]
	v_mfma_i32_16x16x64_i8 v[22:25], v[182:185], v[216:219], v[22:25]
	v_mfma_i32_16x16x64_i8 v[14:17], v[190:193], v[216:219], v[14:17]
	v_mfma_i32_16x16x64_i8 v[6:9], v[182:185], v[224:227], v[6:9]
	v_mfma_i32_16x16x64_i8 v[2:5], v[190:193], v[224:227], v[2:5]
	v_mfma_i32_16x16x64_i8 v[54:57], v[186:189], v[202:205], v[54:57]
	v_mfma_i32_16x16x64_i8 v[46:49], v[194:197], v[202:205], v[46:49]
	v_mfma_i32_16x16x64_i8 v[38:41], v[186:189], v[212:215], v[38:41]
	v_mfma_i32_16x16x64_i8 v[34:37], v[194:197], v[212:215], v[34:37]
	v_mfma_i32_16x16x64_i8 v[22:25], v[186:189], v[220:223], v[22:25]
	v_mfma_i32_16x16x64_i8 v[14:17], v[194:197], v[220:223], v[14:17]
	v_mfma_i32_16x16x64_i8 v[6:9], v[186:189], v[228:231], v[6:9]
	v_mfma_i32_16x16x64_i8 v[2:5], v[194:197], v[228:231], v[2:5]
	s_barrier
	s_add_i32 s63, 0, 0x18000
	v_add_u32_e32 v154, s63, v175
	s_add_i32 s64, 0, 0x1c000
	ds_read_b128 v[90:93], v154
	ds_read_b128 v[98:101], v154 offset:1024
	ds_read_b128 v[102:105], v154 offset:2048
	ds_read_b128 v[160:163], v154 offset:3072
	v_add_u32_e32 v154, s64, v175
	ds_read_b128 v[182:185], v154
	ds_read_b128 v[186:189], v154 offset:1024
	ds_read_b128 v[190:193], v154 offset:2048
	ds_read_b128 v[194:197], v154 offset:3072
	s_add_u32 s40, s40, 0x180000
	s_addc_u32 s41, s41, 0
	s_mov_b32 m0, s50
	v_lshl_add_u64 v[176:177], s[40:41], 0, v[144:145]
	ds_read_b128 v[198:201], v207 offset:32768
	ds_read_b128 v[202:205], v207 offset:33792
	ds_read_b128 v[208:211], v207 offset:34816
	ds_read_b128 v[212:215], v207 offset:35840
	ds_read_b128 v[216:219], v207 offset:36864
	ds_read_b128 v[220:223], v207 offset:37888
	ds_read_b128 v[224:227], v207 offset:38912
	ds_read_b128 v[228:231], v207 offset:39936
	global_load_lds_dwordx4 v[176:177], off
	v_lshl_add_u64 v[176:177], s[40:41], 0, v[142:143]
	s_mov_b32 m0, s51
	s_nop 0
	global_load_lds_dwordx4 v[176:177], off
	s_waitcnt vmcnt(8)
	s_waitcnt lgkmcnt(0)
	s_barrier
	v_mfma_i32_16x16x64_i8 v[94:97], v[90:93], v[198:201], v[94:97]
	v_mfma_i32_16x16x64_i8 v[138:141], v[102:105], v[198:201], v[138:141]
	v_mfma_i32_16x16x64_i8 v[130:133], v[90:93], v[208:211], v[130:133]
	v_mfma_i32_16x16x64_i8 v[122:125], v[102:105], v[208:211], v[122:125]
	v_mfma_i32_16x16x64_i8 v[110:113], v[90:93], v[216:219], v[110:113]
	v_mfma_i32_16x16x64_i8 v[106:109], v[102:105], v[216:219], v[106:109]
	v_mfma_i32_16x16x64_i8 v[82:85], v[90:93], v[224:227], v[82:85]
	v_mfma_i32_16x16x64_i8 v[74:77], v[102:105], v[224:227], v[74:77]
	v_mfma_i32_16x16x64_i8 v[94:97], v[98:101], v[202:205], v[94:97]
	v_mfma_i32_16x16x64_i8 v[138:141], v[160:163], v[202:205], v[138:141]
	v_mfma_i32_16x16x64_i8 v[130:133], v[98:101], v[212:215], v[130:133]
	v_mfma_i32_16x16x64_i8 v[122:125], v[160:163], v[212:215], v[122:125]
	v_mfma_i32_16x16x64_i8 v[110:113], v[98:101], v[220:223], v[110:113]
	v_mfma_i32_16x16x64_i8 v[106:109], v[160:163], v[220:223], v[106:109]
	v_mfma_i32_16x16x64_i8 v[82:85], v[98:101], v[228:231], v[82:85]
	v_mfma_i32_16x16x64_i8 v[74:77], v[160:163], v[228:231], v[74:77]
	v_mfma_i32_16x16x64_i8 v[134:137], v[182:185], v[198:201], v[134:137]
	v_mfma_i32_16x16x64_i8 v[126:129], v[190:193], v[198:201], v[126:129]
	v_mfma_i32_16x16x64_i8 v[118:121], v[182:185], v[208:211], v[118:121]
	v_mfma_i32_16x16x64_i8 v[114:117], v[190:193], v[208:211], v[114:117]
	v_mfma_i32_16x16x64_i8 v[86:89], v[182:185], v[216:219], v[86:89]
	v_mfma_i32_16x16x64_i8 v[78:81], v[190:193], v[216:219], v[78:81]
	v_mfma_i32_16x16x64_i8 v[70:73], v[182:185], v[224:227], v[70:73]
	v_mfma_i32_16x16x64_i8 v[66:69], v[190:193], v[224:227], v[66:69]
	v_mfma_i32_16x16x64_i8 v[134:137], v[186:189], v[202:205], v[134:137]
	v_mfma_i32_16x16x64_i8 v[126:129], v[194:197], v[202:205], v[126:129]
	v_mfma_i32_16x16x64_i8 v[118:121], v[186:189], v[212:215], v[118:121]
	v_mfma_i32_16x16x64_i8 v[114:117], v[194:197], v[212:215], v[114:117]
	v_mfma_i32_16x16x64_i8 v[86:89], v[186:189], v[220:223], v[86:89]
	v_mfma_i32_16x16x64_i8 v[78:81], v[194:197], v[220:223], v[78:81]
	v_mfma_i32_16x16x64_i8 v[70:73], v[186:189], v[228:231], v[70:73]
	v_mfma_i32_16x16x64_i8 v[66:69], v[194:197], v[228:231], v[66:69]
	s_barrier
; #define PG8_STAGE(bufoff, gbase, voff) do { _Pragma("unroll") for (int _i = 0; _i < 2; ++_i) \
;         __builtin_amdgcn_global_load_lds((const unsigned*)((const char*)(gbase) + (voff)[_i]), (LAS unsigned*)(lds + (bufoff) + ldsw + _i * 8192), 16, 0, 0); } while (0)
; #define PG8_LDA(dst, b, h) do { _Pragma("unroll") for (int m = 0; m < 4; ++m) _Pragma("unroll") for (int k = 0; k < 2; ++k) dst[m][k] = *(const LAS bf16x8*)(lds + PG8_SA(b, h) + aoff + m * 2048 + k * 1024); } while (0)
; #define PG8_WAIT_V(n) asm volatile("s_waitcnt vmcnt(" #n ")" ::: "memory")
; #define PG8_WAIT_L(n) asm volatile("s_waitcnt lgkmcnt(" #n ")" ::: "memory")
; #define PG8_BAR __builtin_amdgcn_s_barrier()
; #define PG8_SCHED __builtin_amdgcn_sched_barrier(0)
; template <class Epi, class Geom, class Sched, bool ALIGN_EPI, bool I8 = false>
; __device__ __forceinline__ void gemm_phase(LAS unsigned char* lds, const Gemm g, const Sched& S, const Epi& E) {
;     ...
;             PG8_LDA(At, 1, 1); PG8_STAGE(PG8_SB(1, 0), b3, voffB); PG8_STAGE(PG8_SB(1, 1), b3 + hsB, voffB); PG8_STAGE(PG8_SA(1, 0), a3, voffA);
;             PG8_WAIT_V(8); PG8_WAIT_L(0); PG8_BAR; PG8_MMA(1, 0, At, B0); PG8_MMA(1, 1, At, B1); PG8_BAR; PG8_SCHED;
;         }
;         if constexpr (ALIGN_EPI) { if (wr == 0) PG8_BAR; }
	s_add_i32 s40, s63, s46
	v_lshl_add_u64 v[152:153], v[152:153], 0, s[20:21]
	s_mov_b32 m0, s40
	ds_read_b128 v[198:201], v207 offset:49152
	ds_read_b128 v[202:205], v207 offset:50176
	ds_read_b128 v[208:211], v207 offset:51200
	ds_read_b128 v[212:215], v207 offset:52224
	ds_read_b128 v[216:219], v207 offset:53248
	ds_read_b128 v[220:223], v207 offset:54272
	ds_read_b128 v[224:227], v207 offset:55296
	ds_read_b128 v[228:231], v207 offset:56320
	global_load_lds_dwordx4 v[152:153], off
	s_add_i32 m0, s40, 0x2000
	s_add_u32 s38, s38, 0x180080
	v_lshl_add_u64 v[152:153], v[156:157], 0, s[20:21]
	s_addc_u32 s39, s39, 0
	s_add_i32 s40, s64, s46
	global_load_lds_dwordx4 v[152:153], off
	v_lshl_add_u64 v[152:153], s[38:39], 0, v[144:145]
	s_mov_b32 m0, s40
	s_nop 0
	global_load_lds_dwordx4 v[152:153], off
	v_lshl_add_u64 v[152:153], s[38:39], 0, v[142:143]
	s_add_i32 m0, s40, 0x2000
	s_nop 0
	global_load_lds_dwordx4 v[152:153], off
	v_lshl_add_u64 v[152:153], v[166:167], 0, s[20:21]
	s_mov_b32 m0, s52
	s_nop 0
	global_load_lds_dwordx4 v[152:153], off
	v_lshl_add_u64 v[152:153], v[170:171], 0, s[20:21]
	s_mov_b32 m0, s53
	s_nop 0
	global_load_lds_dwordx4 v[152:153], off
	s_waitcnt vmcnt(8)
	s_waitcnt lgkmcnt(0)
	s_barrier
	v_mfma_i32_16x16x64_i8 v[62:65], v[90:93], v[198:201], v[62:65]
	v_mfma_i32_16x16x64_i8 v[58:61], v[102:105], v[198:201], v[58:61]
	v_mfma_i32_16x16x64_i8 v[50:53], v[90:93], v[208:211], v[50:53]
	v_mfma_i32_16x16x64_i8 v[42:45], v[102:105], v[208:211], v[42:45]
	v_mfma_i32_16x16x64_i8 v[30:33], v[90:93], v[216:219], v[30:33]
	v_mfma_i32_16x16x64_i8 v[26:29], v[102:105], v[216:219], v[26:29]
	v_mfma_i32_16x16x64_i8 v[18:21], v[90:93], v[224:227], v[18:21]
	v_mfma_i32_16x16x64_i8 v[10:13], v[102:105], v[224:227], v[10:13]
	v_mfma_i32_16x16x64_i8 v[62:65], v[98:101], v[202:205], v[62:65]
	v_mfma_i32_16x16x64_i8 v[58:61], v[160:163], v[202:205], v[58:61]
	v_mfma_i32_16x16x64_i8 v[50:53], v[98:101], v[212:215], v[50:53]
	v_mfma_i32_16x16x64_i8 v[42:45], v[160:163], v[212:215], v[42:45]
	v_mfma_i32_16x16x64_i8 v[30:33], v[98:101], v[220:223], v[30:33]
	v_mfma_i32_16x16x64_i8 v[26:29], v[160:163], v[220:223], v[26:29]
	v_mfma_i32_16x16x64_i8 v[18:21], v[98:101], v[228:231], v[18:21]
	v_mfma_i32_16x16x64_i8 v[10:13], v[160:163], v[228:231], v[10:13]
	v_mfma_i32_16x16x64_i8 v[54:57], v[182:185], v[198:201], v[54:57]
	v_mfma_i32_16x16x64_i8 v[46:49], v[190:193], v[198:201], v[46:49]
	v_mfma_i32_16x16x64_i8 v[38:41], v[182:185], v[208:211], v[38:41]
	v_mfma_i32_16x16x64_i8 v[34:37], v[190:193], v[208:211], v[34:37]
	v_mfma_i32_16x16x64_i8 v[22:25], v[182:185], v[216:219], v[22:25]
	v_mfma_i32_16x16x64_i8 v[14:17], v[190:193], v[216:219], v[14:17]
	v_mfma_i32_16x16x64_i8 v[6:9], v[182:185], v[224:227], v[6:9]
	v_mfma_i32_16x16x64_i8 v[2:5], v[190:193], v[224:227], v[2:5]
	v_mfma_i32_16x16x64_i8 v[54:57], v[186:189], v[202:205], v[54:57]
	v_mfma_i32_16x16x64_i8 v[46:49], v[194:197], v[202:205], v[46:49]
	v_mfma_i32_16x16x64_i8 v[38:41], v[186:189], v[212:215], v[38:41]
	v_mfma_i32_16x16x64_i8 v[34:37], v[194:197], v[212:215], v[34:37]
	v_mfma_i32_16x16x64_i8 v[22:25], v[186:189], v[220:223], v[22:25]
	v_mfma_i32_16x16x64_i8 v[14:17], v[194:197], v[220:223], v[14:17]
	v_mfma_i32_16x16x64_i8 v[6:9], v[186:189], v[228:231], v[6:9]
	v_mfma_i32_16x16x64_i8 v[2:5], v[194:197], v[228:231], v[2:5]
	s_barrier
	s_add_i32 s62, s62, 2
	s_add_u32 s36, s36, 0x100
	s_addc_u32 s37, s37, 0
	s_add_u32 s60, s60, 0x100
	s_addc_u32 s61, s61, 0
	s_cmpk_gt_u32 s62, 0x5d
	s_cbranch_scc0 .LBB0_2872
	s_and_b64 vcc, exec, s[22:23]
	s_cbranch_vccz .LBB0_2875
	s_barrier

; #define PG8_STAGE(bufoff, gbase, voff) do { _Pragma("unroll") for (int _i = 0; _i < 2; ++_i) \
;         __builtin_amdgcn_global_load_lds((const unsigned*)((const char*)(gbase) + (voff)[_i]), (LAS unsigned*)(lds + (bufoff) + ldsw + _i * 8192), 16, 0, 0); } while (0)
; #define PG8_LDA(dst, b, h) do { _Pragma("unroll") for (int m = 0; m < 4; ++m) _Pragma("unroll") for (int k = 0; k < 2; ++k) dst[m][k] = *(const LAS bf16x8*)(lds + PG8_SA(b, h) + aoff + m * 2048 + k * 1024); } while (0)
; #define PG8_LDB(dst, b, h) do { _Pragma("unroll") for (int n = 0; n < 2; ++n) _Pragma("unroll") for (int k = 0; k < 2; ++k) dst[n][k] = *(const LAS bf16x8*)(lds + PG8_SB(b, h) + boff + n * 2048 + k * 1024); } while (0)
; #define PG8_WAIT_V(n) asm volatile("s_waitcnt vmcnt(" #n ")" ::: "memory")
; #define PG8_WAIT_L(n) asm volatile("s_waitcnt lgkmcnt(" #n ")" ::: "memory")
; #define PG8_BAR __builtin_amdgcn_s_barrier()
; #define PG8_SCHED __builtin_amdgcn_sched_barrier(0)
; template <class Epi, class Geom, class Sched, bool ALIGN_EPI, bool I8 = false>
; __device__ __forceinline__ void gemm_phase(LAS unsigned char* lds, const Gemm g, const Sched& S, const Epi& E) {
;     ...
;             PG8_LDB(B0, 0, 0); PG8_LDB(B1, 0, 1); PG8_SCHED; PG8_LDA(At, 0, 0); PG8_STAGE(PG8_SA(1, 1), a1 + hsA, voffA);
;             PG8_WAIT_V(8); PG8_WAIT_L(0); PG8_BAR; PG8_MMA(0, 0, At, B0); PG8_MMA(0, 1, At, B1); PG8_BAR; PG8_SCHED;
;             PG8_LDA(At, 0, 1); PG8_STAGE(PG8_SB(0, 0), b2, voffB); PG8_STAGE(PG8_SB(0, 1), b2 + hsB, voffB); PG8_STAGE(PG8_SA(0, 0), a2, voffA);
;             PG8_WAIT_V(8); PG8_WAIT_L(0); PG8_BAR; PG8_MMA(1, 0, At, B0); PG8_MMA(1, 1, At, B1); PG8_BAR; PG8_SCHED;
.LBB0_2884:
	ds_read_b128 v[118:121], v1
	ds_read_b128 v[148:151], v1 offset:1024
	ds_read_b128 v[152:155], v1 offset:2048
	ds_read_b128 v[156:159], v1 offset:3072
	ds_read_b128 v[160:163], v114
	ds_read_b128 v[164:167], v114 offset:1024
	ds_read_b128 v[168:171], v114 offset:2048
	ds_read_b128 v[172:175], v114 offset:3072
	s_add_u32 s14, s12, 0x100
	s_addc_u32 s15, s13, 0
	s_cmp_lg_u32 s33, 8
	s_cselect_b32 s16, s14, 0
	s_cselect_b32 s17, s15, 0
	s_add_u32 s18, s2, s16
	s_addc_u32 s19, s3, s17
	s_add_u32 s16, s0, s16
	s_addc_u32 s17, s1, s17
	s_mov_b32 m0, s34
	v_lshl_add_u64 v[208:209], v[110:111], 0, s[12:13]
	ds_read_b128 v[176:179], v115
	ds_read_b128 v[180:183], v115 offset:1024
	ds_read_b128 v[184:187], v115 offset:2048
	ds_read_b128 v[188:191], v115 offset:3072
	ds_read_b128 v[192:195], v115 offset:4096
	ds_read_b128 v[196:199], v115 offset:5120
	ds_read_b128 v[200:203], v115 offset:6144
	ds_read_b128 v[204:207], v115 offset:7168
	global_load_lds_dwordx4 v[208:209], off
	v_lshl_add_u64 v[208:209], v[112:113], 0, s[12:13]
	s_mov_b32 m0, s35
	s_nop 0
	global_load_lds_dwordx4 v[208:209], off
	s_waitcnt vmcnt(8)
	s_waitcnt lgkmcnt(0)
	s_barrier
	v_mfma_i32_16x16x64_i8 v[142:145], v[118:121], v[176:179], v[142:145]
	v_mfma_i32_16x16x64_i8 v[138:141], v[152:155], v[176:179], v[138:141]
	v_mfma_i32_16x16x64_i8 v[126:129], v[118:121], v[184:187], v[126:129]
	v_mfma_i32_16x16x64_i8 v[122:125], v[152:155], v[184:187], v[122:125]
	v_mfma_i32_16x16x64_i8 v[94:97], v[118:121], v[192:195], v[94:97]
	v_mfma_i32_16x16x64_i8 v[90:93], v[152:155], v[192:195], v[90:93]
	v_mfma_i32_16x16x64_i8 v[78:81], v[118:121], v[200:203], v[78:81]
	v_mfma_i32_16x16x64_i8 v[74:77], v[152:155], v[200:203], v[74:77]
	v_mfma_i32_16x16x64_i8 v[142:145], v[148:151], v[180:183], v[142:145]
	v_mfma_i32_16x16x64_i8 v[138:141], v[156:159], v[180:183], v[138:141]
	v_mfma_i32_16x16x64_i8 v[126:129], v[148:151], v[188:191], v[126:129]
	v_mfma_i32_16x16x64_i8 v[122:125], v[156:159], v[188:191], v[122:125]
	v_mfma_i32_16x16x64_i8 v[94:97], v[148:151], v[196:199], v[94:97]
	v_mfma_i32_16x16x64_i8 v[90:93], v[156:159], v[196:199], v[90:93]
	v_mfma_i32_16x16x64_i8 v[78:81], v[148:151], v[204:207], v[78:81]
	v_mfma_i32_16x16x64_i8 v[74:77], v[156:159], v[204:207], v[74:77]
	v_mfma_i32_16x16x64_i8 v[134:137], v[160:163], v[176:179], v[134:137]
	v_mfma_i32_16x16x64_i8 v[130:133], v[168:171], v[176:179], v[130:133]
	v_mfma_i32_16x16x64_i8 v[102:105], v[160:163], v[184:187], v[102:105]
	v_mfma_i32_16x16x64_i8 v[98:101], v[168:171], v[184:187], v[98:101]
	v_mfma_i32_16x16x64_i8 v[86:89], v[160:163], v[192:195], v[86:89]
	v_mfma_i32_16x16x64_i8 v[82:85], v[168:171], v[192:195], v[82:85]
	v_mfma_i32_16x16x64_i8 v[70:73], v[160:163], v[200:203], v[70:73]
	v_mfma_i32_16x16x64_i8 v[66:69], v[168:171], v[200:203], v[66:69]
	v_mfma_i32_16x16x64_i8 v[134:137], v[164:167], v[180:183], v[134:137]
	v_mfma_i32_16x16x64_i8 v[130:133], v[172:175], v[180:183], v[130:133]
	v_mfma_i32_16x16x64_i8 v[102:105], v[164:167], v[188:191], v[102:105]
	v_mfma_i32_16x16x64_i8 v[98:101], v[172:175], v[188:191], v[98:101]
	v_mfma_i32_16x16x64_i8 v[86:89], v[164:167], v[196:199], v[86:89]
	v_mfma_i32_16x16x64_i8 v[82:85], v[172:175], v[196:199], v[82:85]
	v_mfma_i32_16x16x64_i8 v[70:73], v[164:167], v[204:207], v[70:73]
	v_mfma_i32_16x16x64_i8 v[66:69], v[172:175], v[204:207], v[66:69]
	s_barrier
	s_mov_b32 m0, s36
	v_lshl_add_u64 v[208:209], s[16:17], 0, v[108:109]
	s_add_u32 s12, s16, 0x180000
	ds_read_b128 v[176:179], v115 offset:16384
	ds_read_b128 v[180:183], v115 offset:17408
	ds_read_b128 v[184:187], v115 offset:18432
	ds_read_b128 v[188:191], v115 offset:19456
	ds_read_b128 v[192:195], v115 offset:20480
	ds_read_b128 v[196:199], v115 offset:21504
	ds_read_b128 v[200:203], v115 offset:22528
	ds_read_b128 v[204:207], v115 offset:23552
	global_load_lds_dwordx4 v[208:209], off
	v_lshl_add_u64 v[210:211], s[16:17], 0, v[106:107]
	s_mov_b32 m0, s37
	s_addc_u32 s13, s17, 0
	global_load_lds_dwordx4 v[210:211], off
	v_lshl_add_u64 v[212:213], s[12:13], 0, v[108:109]
	s_mov_b32 m0, s38
	v_lshl_add_u64 v[214:215], s[18:19], 0, v[106:107]
	global_load_lds_dwordx4 v[212:213], off
	v_lshl_add_u64 v[212:213], s[12:13], 0, v[106:107]
	s_mov_b32 m0, s39
	s_nop 0
	global_load_lds_dwordx4 v[212:213], off
	v_lshl_add_u64 v[212:213], s[18:19], 0, v[108:109]
	s_mov_b32 m0, s26
	s_nop 0
	global_load_lds_dwordx4 v[212:213], off
	s_mov_b32 m0, s27
	s_nop 0
	global_load_lds_dwordx4 v[214:215], off
	s_waitcnt vmcnt(8)
	s_waitcnt lgkmcnt(0)
	s_barrier
	v_mfma_i32_16x16x64_i8 v[62:65], v[118:121], v[176:179], v[62:65]
	v_mfma_i32_16x16x64_i8 v[58:61], v[152:155], v[176:179], v[58:61]
	v_mfma_i32_16x16x64_i8 v[46:49], v[118:121], v[184:187], v[46:49]
	v_mfma_i32_16x16x64_i8 v[42:45], v[152:155], v[184:187], v[42:45]
	v_mfma_i32_16x16x64_i8 v[30:33], v[118:121], v[192:195], v[30:33]
	v_mfma_i32_16x16x64_i8 v[26:29], v[152:155], v[192:195], v[26:29]
	v_mfma_i32_16x16x64_i8 v[14:17], v[118:121], v[200:203], v[14:17]
	v_mfma_i32_16x16x64_i8 v[10:13], v[152:155], v[200:203], v[10:13]
	v_mfma_i32_16x16x64_i8 v[62:65], v[148:151], v[180:183], v[62:65]
	v_mfma_i32_16x16x64_i8 v[58:61], v[156:159], v[180:183], v[58:61]
	v_mfma_i32_16x16x64_i8 v[46:49], v[148:151], v[188:191], v[46:49]
	v_mfma_i32_16x16x64_i8 v[42:45], v[156:159], v[188:191], v[42:45]
	v_mfma_i32_16x16x64_i8 v[30:33], v[148:151], v[196:199], v[30:33]
	v_mfma_i32_16x16x64_i8 v[26:29], v[156:159], v[196:199], v[26:29]
	v_mfma_i32_16x16x64_i8 v[14:17], v[148:151], v[204:207], v[14:17]
	v_mfma_i32_16x16x64_i8 v[10:13], v[156:159], v[204:207], v[10:13]
	v_mfma_i32_16x16x64_i8 v[54:57], v[160:163], v[176:179], v[54:57]
	v_mfma_i32_16x16x64_i8 v[50:53], v[168:171], v[176:179], v[50:53]
	v_mfma_i32_16x16x64_i8 v[38:41], v[160:163], v[184:187], v[38:41]
	v_mfma_i32_16x16x64_i8 v[34:37], v[168:171], v[184:187], v[34:37]
	v_mfma_i32_16x16x64_i8 v[22:25], v[160:163], v[192:195], v[22:25]
	v_mfma_i32_16x16x64_i8 v[18:21], v[168:171], v[192:195], v[18:21]
	v_mfma_i32_16x16x64_i8 v[6:9], v[160:163], v[200:203], v[6:9]
	v_mfma_i32_16x16x64_i8 v[2:5], v[168:171], v[200:203], v[2:5]
	v_mfma_i32_16x16x64_i8 v[54:57], v[164:167], v[180:183], v[54:57]
	v_mfma_i32_16x16x64_i8 v[50:53], v[172:175], v[180:183], v[50:53]
	v_mfma_i32_16x16x64_i8 v[38:41], v[164:167], v[188:191], v[38:41]
	v_mfma_i32_16x16x64_i8 v[34:37], v[172:175], v[188:191], v[34:37]
	v_mfma_i32_16x16x64_i8 v[22:25], v[164:167], v[196:199], v[22:25]
	v_mfma_i32_16x16x64_i8 v[18:21], v[172:175], v[196:199], v[18:21]
	v_mfma_i32_16x16x64_i8 v[6:9], v[164:167], v[204:207], v[6:9]
	v_mfma_i32_16x16x64_i8 v[2:5], v[172:175], v[204:207], v[2:5]
	s_barrier
; #define PG8_STAGE(bufoff, gbase, voff) do { _Pragma("unroll") for (int _i = 0; _i < 2; ++_i) \
;         __builtin_amdgcn_global_load_lds((const unsigned*)((const char*)(gbase) + (voff)[_i]), (LAS unsigned*)(lds + (bufoff) + ldsw + _i * 8192), 16, 0, 0); } while (0)
; #define PG8_LDA(dst, b, h) do { _Pragma("unroll") for (int m = 0; m < 4; ++m) _Pragma("unroll") for (int k = 0; k < 2; ++k) dst[m][k] = *(const LAS bf16x8*)(lds + PG8_SA(b, h) + aoff + m * 2048 + k * 1024); } while (0)
; #define PG8_LDB(dst, b, h) do { _Pragma("unroll") for (int n = 0; n < 2; ++n) _Pragma("unroll") for (int k = 0; k < 2; ++k) dst[n][k] = *(const LAS bf16x8*)(lds + PG8_SB(b, h) + boff + n * 2048 + k * 1024); } while (0)
; #define PG8_WAIT_V(n) asm volatile("s_waitcnt vmcnt(" #n ")" ::: "memory")
; #define PG8_WAIT_L(n) asm volatile("s_waitcnt lgkmcnt(" #n ")" ::: "memory")
; #define PG8_BAR __builtin_amdgcn_s_barrier()
; #define PG8_SCHED __builtin_amdgcn_sched_barrier(0)
; template <class Epi, class Geom, class Sched, bool ALIGN_EPI, bool I8 = false>
; __device__ __forceinline__ void gemm_phase(LAS unsigned char* lds, const Gemm g, const Sched& S, const Epi& E) {
;     ...
;             PG8_LDB(B0, 1, 0); PG8_LDB(B1, 1, 1); PG8_SCHED; PG8_LDA(At, 1, 0); PG8_STAGE(PG8_SA(0, 1), a2 + hsA, voffA);
;             PG8_WAIT_V(8); PG8_WAIT_L(0); PG8_BAR; PG8_MMA(0, 0, At, B0); PG8_MMA(0, 1, At, B1); PG8_BAR; PG8_SCHED;
;             PG8_LDA(At, 1, 1); PG8_STAGE(PG8_SB(1, 0), b3, voffB); PG8_STAGE(PG8_SB(1, 1), b3 + hsB, voffB); PG8_STAGE(PG8_SA(1, 0), a3, voffA);
;             PG8_WAIT_V(8); PG8_WAIT_L(0); PG8_BAR; PG8_MMA(1, 0, At, B0); PG8_MMA(1, 1, At, B1); PG8_BAR; PG8_SCHED;
;         }
;         if constexpr (ALIGN_EPI) { if (wr == 0) PG8_BAR; }
	ds_read_b128 v[118:121], v116
	ds_read_b128 v[148:151], v116 offset:1024
	ds_read_b128 v[152:155], v116 offset:2048
	ds_read_b128 v[156:159], v116 offset:3072
	ds_read_b128 v[160:163], v117
	ds_read_b128 v[164:167], v117 offset:1024
	ds_read_b128 v[168:171], v117 offset:2048
	ds_read_b128 v[172:175], v117 offset:3072
	s_add_u32 s12, s18, 0x180000
	s_addc_u32 s13, s19, 0
	s_mov_b32 m0, s28
	v_lshl_add_u64 v[216:217], s[12:13], 0, v[108:109]
	ds_read_b128 v[176:179], v115 offset:32768
	ds_read_b128 v[180:183], v115 offset:33792
	ds_read_b128 v[184:187], v115 offset:34816
	ds_read_b128 v[188:191], v115 offset:35840
	ds_read_b128 v[192:195], v115 offset:36864
	ds_read_b128 v[196:199], v115 offset:37888
	ds_read_b128 v[200:203], v115 offset:38912
	ds_read_b128 v[204:207], v115 offset:39936
	global_load_lds_dwordx4 v[216:217], off
	v_lshl_add_u64 v[216:217], s[12:13], 0, v[106:107]
	s_mov_b32 m0, s29
	s_nop 0
	global_load_lds_dwordx4 v[216:217], off
	s_waitcnt vmcnt(8)
	s_waitcnt lgkmcnt(0)
	s_barrier
	v_mfma_i32_16x16x64_i8 v[142:145], v[118:121], v[176:179], v[142:145]
	v_mfma_i32_16x16x64_i8 v[138:141], v[152:155], v[176:179], v[138:141]
	v_mfma_i32_16x16x64_i8 v[126:129], v[118:121], v[184:187], v[126:129]
	v_mfma_i32_16x16x64_i8 v[122:125], v[152:155], v[184:187], v[122:125]
	v_mfma_i32_16x16x64_i8 v[94:97], v[118:121], v[192:195], v[94:97]
	v_mfma_i32_16x16x64_i8 v[90:93], v[152:155], v[192:195], v[90:93]
	v_mfma_i32_16x16x64_i8 v[78:81], v[118:121], v[200:203], v[78:81]
	v_mfma_i32_16x16x64_i8 v[74:77], v[152:155], v[200:203], v[74:77]
	v_mfma_i32_16x16x64_i8 v[142:145], v[148:151], v[180:183], v[142:145]
	v_mfma_i32_16x16x64_i8 v[138:141], v[156:159], v[180:183], v[138:141]
	v_mfma_i32_16x16x64_i8 v[126:129], v[148:151], v[188:191], v[126:129]
	v_mfma_i32_16x16x64_i8 v[122:125], v[156:159], v[188:191], v[122:125]
	v_mfma_i32_16x16x64_i8 v[94:97], v[148:151], v[196:199], v[94:97]
	v_mfma_i32_16x16x64_i8 v[90:93], v[156:159], v[196:199], v[90:93]
	v_mfma_i32_16x16x64_i8 v[78:81], v[148:151], v[204:207], v[78:81]
	v_mfma_i32_16x16x64_i8 v[74:77], v[156:159], v[204:207], v[74:77]
	v_mfma_i32_16x16x64_i8 v[134:137], v[160:163], v[176:179], v[134:137]
	v_mfma_i32_16x16x64_i8 v[130:133], v[168:171], v[176:179], v[130:133]
	v_mfma_i32_16x16x64_i8 v[102:105], v[160:163], v[184:187], v[102:105]
	v_mfma_i32_16x16x64_i8 v[98:101], v[168:171], v[184:187], v[98:101]
	v_mfma_i32_16x16x64_i8 v[86:89], v[160:163], v[192:195], v[86:89]
	v_mfma_i32_16x16x64_i8 v[82:85], v[168:171], v[192:195], v[82:85]
	v_mfma_i32_16x16x64_i8 v[70:73], v[160:163], v[200:203], v[70:73]
	v_mfma_i32_16x16x64_i8 v[66:69], v[168:171], v[200:203], v[66:69]
	v_mfma_i32_16x16x64_i8 v[134:137], v[164:167], v[180:183], v[134:137]
	v_mfma_i32_16x16x64_i8 v[130:133], v[172:175], v[180:183], v[130:133]
	v_mfma_i32_16x16x64_i8 v[102:105], v[164:167], v[188:191], v[102:105]
	v_mfma_i32_16x16x64_i8 v[98:101], v[172:175], v[188:191], v[98:101]
	v_mfma_i32_16x16x64_i8 v[86:89], v[164:167], v[196:199], v[86:89]
	v_mfma_i32_16x16x64_i8 v[82:85], v[172:175], v[196:199], v[82:85]
	v_mfma_i32_16x16x64_i8 v[70:73], v[164:167], v[204:207], v[70:73]
	v_mfma_i32_16x16x64_i8 v[66:69], v[172:175], v[204:207], v[66:69]
	s_barrier
	s_mov_b32 m0, s40
	v_lshl_add_u64 v[208:209], v[208:209], 0, s[4:5]
	s_add_u32 s12, s16, 0x180080
	ds_read_b128 v[176:179], v115 offset:49152
	ds_read_b128 v[180:183], v115 offset:50176
	ds_read_b128 v[184:187], v115 offset:51200
	ds_read_b128 v[188:191], v115 offset:52224
	ds_read_b128 v[192:195], v115 offset:53248
	ds_read_b128 v[196:199], v115 offset:54272
	ds_read_b128 v[200:203], v115 offset:55296
	ds_read_b128 v[204:207], v115 offset:56320
	global_load_lds_dwordx4 v[208:209], off
	v_lshl_add_u64 v[208:209], v[210:211], 0, s[4:5]
	s_mov_b32 m0, s41
	s_addc_u32 s13, s17, 0
	global_load_lds_dwordx4 v[208:209], off
	v_lshl_add_u64 v[208:209], s[12:13], 0, v[108:109]
	s_mov_b32 m0, s42
	s_nop 0
	global_load_lds_dwordx4 v[208:209], off
	v_lshl_add_u64 v[208:209], s[12:13], 0, v[106:107]
	s_mov_b32 m0, s43
	s_nop 0
	global_load_lds_dwordx4 v[208:209], off
	v_lshl_add_u64 v[208:209], v[212:213], 0, s[4:5]
	s_mov_b32 m0, s30
	s_nop 0
	global_load_lds_dwordx4 v[208:209], off
	v_lshl_add_u64 v[208:209], v[214:215], 0, s[4:5]
	s_mov_b32 m0, s31
	s_nop 0
	global_load_lds_dwordx4 v[208:209], off
	s_waitcnt vmcnt(8)
	s_waitcnt lgkmcnt(0)
	s_barrier
	v_mfma_i32_16x16x64_i8 v[62:65], v[118:121], v[176:179], v[62:65]
	v_mfma_i32_16x16x64_i8 v[58:61], v[152:155], v[176:179], v[58:61]
	v_mfma_i32_16x16x64_i8 v[46:49], v[118:121], v[184:187], v[46:49]
	v_mfma_i32_16x16x64_i8 v[42:45], v[152:155], v[184:187], v[42:45]
	v_mfma_i32_16x16x64_i8 v[30:33], v[118:121], v[192:195], v[30:33]
	v_mfma_i32_16x16x64_i8 v[26:29], v[152:155], v[192:195], v[26:29]
	v_mfma_i32_16x16x64_i8 v[14:17], v[118:121], v[200:203], v[14:17]
	v_mfma_i32_16x16x64_i8 v[10:13], v[152:155], v[200:203], v[10:13]
	v_mfma_i32_16x16x64_i8 v[62:65], v[148:151], v[180:183], v[62:65]
	v_mfma_i32_16x16x64_i8 v[58:61], v[156:159], v[180:183], v[58:61]
	v_mfma_i32_16x16x64_i8 v[46:49], v[148:151], v[188:191], v[46:49]
	v_mfma_i32_16x16x64_i8 v[42:45], v[156:159], v[188:191], v[42:45]
	v_mfma_i32_16x16x64_i8 v[30:33], v[148:151], v[196:199], v[30:33]
	v_mfma_i32_16x16x64_i8 v[26:29], v[156:159], v[196:199], v[26:29]
	v_mfma_i32_16x16x64_i8 v[14:17], v[148:151], v[204:207], v[14:17]
	v_mfma_i32_16x16x64_i8 v[10:13], v[156:159], v[204:207], v[10:13]
	v_mfma_i32_16x16x64_i8 v[54:57], v[160:163], v[176:179], v[54:57]
	v_mfma_i32_16x16x64_i8 v[50:53], v[168:171], v[176:179], v[50:53]
	v_mfma_i32_16x16x64_i8 v[38:41], v[160:163], v[184:187], v[38:41]
	v_mfma_i32_16x16x64_i8 v[34:37], v[168:171], v[184:187], v[34:37]
	v_mfma_i32_16x16x64_i8 v[22:25], v[160:163], v[192:195], v[22:25]
	v_mfma_i32_16x16x64_i8 v[18:21], v[168:171], v[192:195], v[18:21]
	v_mfma_i32_16x16x64_i8 v[6:9], v[160:163], v[200:203], v[6:9]
	v_mfma_i32_16x16x64_i8 v[2:5], v[168:171], v[200:203], v[2:5]
	v_mfma_i32_16x16x64_i8 v[54:57], v[164:167], v[180:183], v[54:57]
	v_mfma_i32_16x16x64_i8 v[50:53], v[172:175], v[180:183], v[50:53]
	v_mfma_i32_16x16x64_i8 v[38:41], v[164:167], v[188:191], v[38:41]
	v_mfma_i32_16x16x64_i8 v[34:37], v[172:175], v[188:191], v[34:37]
	v_mfma_i32_16x16x64_i8 v[22:25], v[164:167], v[196:199], v[22:25]
	v_mfma_i32_16x16x64_i8 v[18:21], v[172:175], v[196:199], v[18:21]
	v_mfma_i32_16x16x64_i8 v[6:9], v[164:167], v[204:207], v[6:9]
	v_mfma_i32_16x16x64_i8 v[2:5], v[172:175], v[204:207], v[2:5]
	s_barrier
	s_add_i32 s33, s33, 2
	s_cmp_gt_u32 s33, 9
	s_mov_b64 s[12:13], s[14:15]
	s_cbranch_scc0 .LBB0_2884
	s_cmpk_lt_u32 s23, 0x100
	s_cbranch_scc0 .LBB0_2887
	s_barrier
